# s30 plus agent-scope (sc1) LDS-DMA loads for the E_GU A operand, whose buffer is also read by GATES earlier in the same barrier epoch
# speedup vs baseline: 1.0091x; 1.0091x over previous
.LBB0_130:
	s_or_b64 exec, exec, s[20:21]
	s_add_i32 s1, s0, 0xfffff000
	s_lshr_b32 s1, s1, 10
	s_add_i32 s1, s1, 1
	s_cmpk_gt_i32 s0, 0xfff
	s_cselect_b32 s1, s1, 0
	s_mul_i32 s15, s12, 3
	s_add_i32 s1, s1, s15
	s_mul_hi_u32 s15, s1, 0xd000
	s_mul_i32 s1, s1, 0xd000
	s_add_u32 s1, s2, s1
	s_addc_u32 s39, s3, s15
	s_ashr_i32 s15, s14, 31
	s_lshl_b64 s[20:21], s[14:15], 2
	s_add_u32 s20, s1, s20
	s_addc_u32 s21, s39, s21
	v_lshl_add_u64 v[0:1], s[20:21], 0, v[116:117]
	v_mov_b32_e32 v87, v117
	v_lshl_add_u64 v[0:1], v[0:1], 0, v[86:87]
	s_mov_b64 s[20:21], 0x18e05800
	s_mov_b32 s1, 0x18e05000
	v_lshl_add_u64 v[2:3], v[0:1], 0, s[20:21]
	v_add_co_u32_e32 v0, vcc, s1, v0
	s_ashr_i32 s20, s0, 7
	s_nop 0
	v_addc_co_u32_e32 v1, vcc, 0, v1, vcc
	global_load_dword v69, v[0:1], off offset:2048
	global_load_dword v68, v[2:3], off offset:128
	global_load_dword v201, v[0:1], off offset:2560
	global_load_dword v200, v[2:3], off offset:640
	s_ashr_i32 s21, s20, 31
	s_lshl_b64 s[20:21], s[20:21], 18
	v_lshl_add_u64 v[64:65], v[80:81], 0, s[20:21]
	s_ashr_i32 s20, s14, 7
	s_ashr_i32 s21, s20, 31
	s_lshl_b64 s[20:21], s[20:21], 18
	v_lshl_add_u64 v[66:67], v[82:83], 0, s[20:21]
	s_mov_b64 s[20:21], -1
	s_andn2_b64 vcc, exec, s[18:19]
	v_add_u32_e32 v108, 0x400, v88
	v_add_u32_e32 v87, 0x2000, v88
	v_add_u32_e32 v79, 0x2400, v88
	v_add_u32_e32 v78, 0x4000, v88
	v_add_u32_e32 v77, 0x4400, v88
	v_add_u32_e32 v76, 0x6000, v88
	v_add_u32_e32 v75, 0x6400, v88
	v_add_u32_e32 v74, 0x8000, v88
	v_add_u32_e32 v73, 0x8400, v88
	v_add_u32_e32 v71, 0xa000, v88
	v_add_u32_e32 v70, 0xa400, v88
	s_cbranch_vccnz .LBB0_132
	v_readfirstlane_b32 s1, v88
	s_mov_b32 m0, s1
	s_mov_b64 s[18:19], 0x400
	v_readfirstlane_b32 s1, v108
	global_load_lds_dwordx4 v[64:65], off sc1
	v_lshl_add_u64 v[0:1], v[64:65], 0, s[18:19]
	s_mov_b32 m0, s1
	v_readfirstlane_b32 s1, v87
	global_load_lds_dwordx4 v[0:1], off sc1
	s_mov_b32 m0, s1
	v_readfirstlane_b32 s1, v79
	global_load_lds_dwordx4 v[66:67], off
	v_lshl_add_u64 v[0:1], v[66:67], 0, s[18:19]
	s_mov_b32 m0, s1
	v_readfirstlane_b32 s1, v78
	global_load_lds_dwordx4 v[0:1], off
	v_lshl_add_u64 v[0:1], v[64:65], 0, s[44:45]
	s_mov_b32 m0, s1
	v_readfirstlane_b32 s1, v77
	global_load_lds_dwordx4 v[0:1], off sc1
	v_lshl_add_u64 v[0:1], v[64:65], 0, s[66:67]
	s_mov_b32 m0, s1
	v_readfirstlane_b32 s1, v76
	global_load_lds_dwordx4 v[0:1], off sc1
	v_lshl_add_u64 v[0:1], v[66:67], 0, s[44:45]
	s_mov_b32 m0, s1
	v_readfirstlane_b32 s1, v75
	global_load_lds_dwordx4 v[0:1], off
	v_lshl_add_u64 v[0:1], v[66:67], 0, s[66:67]
	s_mov_b32 m0, s1
	v_readfirstlane_b32 s1, v74
	global_load_lds_dwordx4 v[0:1], off
	v_lshl_add_u64 v[0:1], v[64:65], 0, s[28:29]
	s_mov_b32 m0, s1
	s_mov_b64 s[18:19], 0x4400
	v_readfirstlane_b32 s1, v73
	global_load_lds_dwordx4 v[0:1], off sc1
	v_lshl_add_u64 v[0:1], v[64:65], 0, s[18:19]
	s_mov_b32 m0, s1
	v_readfirstlane_b32 s1, v71
	global_load_lds_dwordx4 v[0:1], off sc1
	v_lshl_add_u64 v[0:1], v[66:67], 0, s[28:29]
	s_mov_b32 m0, s1
	v_readfirstlane_b32 s1, v70
	global_load_lds_dwordx4 v[0:1], off
	v_lshl_add_u64 v[0:1], v[66:67], 0, s[18:19]
	s_mov_b32 m0, s1
	s_mov_b64 s[20:21], 0
	global_load_lds_dwordx4 v[0:1], off
	s_waitcnt vmcnt(8)

.Lgu_pair:
	s_add_i32 s63, s63, 1
	s_mov_b32 s62, 1
	v_add_u32_e32 v109, v89, v91
	v_add_u32_e32 v114, v90, v91
	v_add_u32_e32 v115, v89, v92
	v_add_u32_e32 v119, v90, v92
	v_add_u32_e32 v121, 0x4000, v114
	v_add_u32_e32 v122, 0x4000, v119
	v_readfirstlane_b32 s50, v88
	s_mov_b64 s[72:73], 0x40000
	s_mov_b64 s[86:87], 0x4000
	s_add_u32 s51, s50, 0x4000
	s_add_u32 s52, s50, 0x8000
	s_add_u32 s53, s50, 0x2000
	s_add_u32 s54, s50, 0x6000
	s_add_u32 s55, s50, 0xa000
	s_add_u32 s56, s50, 0xc000
	s_add_u32 s57, s50, 0xe000
	s_add_u32 s58, s50, 0x12000
	v_lshl_add_u64 v[148:149], v[66:67], 0, s[72:73]
	s_mov_b32 m0, s56
	s_nop 0
	global_load_lds_dwordx4 v[148:149], off
	global_load_lds_dwordx4 v[148:149], off offset:1024
	v_lshl_add_u64 v[148:149], v[148:149], 0, s[44:45]
	s_mov_b32 m0, s57
	s_nop 0
	global_load_lds_dwordx4 v[148:149], off
	global_load_lds_dwordx4 v[148:149], off offset:1024
	v_lshl_add_u64 v[148:149], v[148:149], 0, s[44:45]
	s_mov_b32 m0, s58
	s_nop 0
	global_load_lds_dwordx4 v[148:149], off
	global_load_lds_dwordx4 v[148:149], off offset:1024
	v_lshl_add_u64 v[64:65], v[64:65], 0, s[86:87]
	v_lshl_add_u64 v[66:67], v[66:67], 0, s[86:87]
	s_waitcnt vmcnt(4)
	s_waitcnt lgkmcnt(0)
	s_barrier
	ds_read_b128 v[110:113], v109
	ds_read_b128 v[132:135], v114 offset:8192
	ds_read_b128 v[136:139], v114 offset:10240
	ds_read_b128 v[140:143], v114 offset:49152
	ds_read_b128 v[144:147], v114 offset:51200
	ds_read_b128 v[128:131], v109 offset:2048
	ds_read_b128 v[202:205], v115
	ds_read_b128 v[214:217], v119 offset:8192
	ds_read_b128 v[244:247], v119 offset:10240
	ds_read_b128 v[250:253], v119 offset:49152
	ds_read_b128 v[206:209], v115 offset:2048
	ds_read_b128 v[74:77], v119 offset:51200
	s_waitcnt lgkmcnt(6)
	v_mfma_f32_32x32x16_bf16 v[48:63], v[110:113], v[132:135], 0
	v_mfma_f32_32x32x16_bf16 v[32:47], v[110:113], v[136:139], 0
	v_mfma_f32_32x32x16_bf16 v[150:165], v[110:113], v[140:143], 0
	v_mfma_f32_32x32x16_bf16 v[166:181], v[110:113], v[144:147], 0
	v_mfma_f32_32x32x16_bf16 v[16:31], v[128:131], v[132:135], 0
	v_mfma_f32_32x32x16_bf16 v[0:15], v[128:131], v[136:139], 0
	v_mfma_f32_32x32x16_bf16 v[184:199], v[128:131], v[140:143], 0
	v_mfma_f32_32x32x16_bf16 v[226:241], v[128:131], v[144:147], 0
	s_waitcnt vmcnt(2)
	s_waitcnt lgkmcnt(0)
	s_barrier
	ds_read_b128 v[110:113], v109 offset:16384
	ds_read_b128 v[132:135], v114 offset:24576
	v_mfma_f32_32x32x16_bf16 v[48:63], v[202:205], v[214:217], v[48:63]
	ds_read_b128 v[136:139], v114 offset:26624
	ds_read_b128 v[140:143], v121 offset:40960
	v_mfma_f32_32x32x16_bf16 v[32:47], v[202:205], v[244:247], v[32:47]
	ds_read_b128 v[144:147], v121 offset:43008
	ds_read_b128 v[128:131], v109 offset:18432
	v_mfma_f32_32x32x16_bf16 v[150:165], v[202:205], v[250:253], v[150:165]
	v_mfma_f32_32x32x16_bf16 v[166:181], v[202:205], v[74:77], v[166:181]
	ds_read_b128 v[202:205], v115 offset:16384
	v_mfma_f32_32x32x16_bf16 v[16:31], v[206:209], v[214:217], v[16:31]
	ds_read_b128 v[214:217], v119 offset:24576
	v_mfma_f32_32x32x16_bf16 v[0:15], v[206:209], v[244:247], v[0:15]
	ds_read_b128 v[244:247], v119 offset:26624
	v_mfma_f32_32x32x16_bf16 v[184:199], v[206:209], v[250:253], v[184:199]
	ds_read_b128 v[250:253], v122 offset:40960
	v_mfma_f32_32x32x16_bf16 v[226:241], v[206:209], v[74:77], v[226:241]
	ds_read_b128 v[206:209], v115 offset:18432
	ds_read_b128 v[74:77], v122 offset:43008
	s_waitcnt lgkmcnt(6)
	v_mfma_f32_32x32x16_bf16 v[48:63], v[110:113], v[132:135], v[48:63]
	s_mov_b32 m0, s50
	v_lshl_add_u64 v[64:65], v[64:65], 0, s[44:45]
	global_load_lds_dwordx4 v[64:65], off sc1
	v_mfma_f32_32x32x16_bf16 v[32:47], v[110:113], v[136:139], v[32:47]
	global_load_lds_dwordx4 v[64:65], off offset:1024 sc1
	v_mfma_f32_32x32x16_bf16 v[150:165], v[110:113], v[140:143], v[150:165]
	s_mov_b32 m0, s53
	v_lshl_add_u64 v[66:67], v[66:67], 0, s[44:45]
	global_load_lds_dwordx4 v[66:67], off
	v_mfma_f32_32x32x16_bf16 v[166:181], v[110:113], v[144:147], v[166:181]
	global_load_lds_dwordx4 v[66:67], off offset:1024
	v_mfma_f32_32x32x16_bf16 v[16:31], v[128:131], v[132:135], v[16:31]
	s_mov_b32 m0, s56
	v_lshl_add_u64 v[148:149], v[66:67], 0, s[72:73]
	global_load_lds_dwordx4 v[148:149], off
	v_mfma_f32_32x32x16_bf16 v[0:15], v[128:131], v[136:139], v[0:15]
	global_load_lds_dwordx4 v[148:149], off offset:1024
	v_mfma_f32_32x32x16_bf16 v[184:199], v[128:131], v[140:143], v[184:199]
	v_mfma_f32_32x32x16_bf16 v[226:241], v[128:131], v[144:147], v[226:241]
	s_waitcnt vmcnt(6)
	s_waitcnt lgkmcnt(0)
	s_barrier
	ds_read_b128 v[110:113], v109 offset:32768
	ds_read_b128 v[132:135], v114 offset:40960
	v_mfma_f32_32x32x16_bf16 v[48:63], v[202:205], v[214:217], v[48:63]
	ds_read_b128 v[136:139], v114 offset:43008
	ds_read_b128 v[140:143], v121 offset:57344
	v_mfma_f32_32x32x16_bf16 v[32:47], v[202:205], v[244:247], v[32:47]
	ds_read_b128 v[144:147], v121 offset:59392
	ds_read_b128 v[128:131], v109 offset:34816
	v_mfma_f32_32x32x16_bf16 v[150:165], v[202:205], v[250:253], v[150:165]
	v_mfma_f32_32x32x16_bf16 v[166:181], v[202:205], v[74:77], v[166:181]
	ds_read_b128 v[202:205], v115 offset:32768
	v_mfma_f32_32x32x16_bf16 v[16:31], v[206:209], v[214:217], v[16:31]
	ds_read_b128 v[214:217], v119 offset:40960
	v_mfma_f32_32x32x16_bf16 v[0:15], v[206:209], v[244:247], v[0:15]
	ds_read_b128 v[244:247], v119 offset:43008
	v_mfma_f32_32x32x16_bf16 v[184:199], v[206:209], v[250:253], v[184:199]
	ds_read_b128 v[250:253], v122 offset:57344
	v_mfma_f32_32x32x16_bf16 v[226:241], v[206:209], v[74:77], v[226:241]
	ds_read_b128 v[206:209], v115 offset:34816
	ds_read_b128 v[74:77], v122 offset:59392
	s_waitcnt lgkmcnt(6)
	v_mfma_f32_32x32x16_bf16 v[48:63], v[110:113], v[132:135], v[48:63]
	s_mov_b32 m0, s51
	v_lshl_add_u64 v[64:65], v[64:65], 0, s[44:45]
	global_load_lds_dwordx4 v[64:65], off sc1
	v_mfma_f32_32x32x16_bf16 v[32:47], v[110:113], v[136:139], v[32:47]
	global_load_lds_dwordx4 v[64:65], off offset:1024 sc1
	v_mfma_f32_32x32x16_bf16 v[150:165], v[110:113], v[140:143], v[150:165]
	s_mov_b32 m0, s54
	v_lshl_add_u64 v[66:67], v[66:67], 0, s[44:45]
	global_load_lds_dwordx4 v[66:67], off
	v_mfma_f32_32x32x16_bf16 v[166:181], v[110:113], v[144:147], v[166:181]
	global_load_lds_dwordx4 v[66:67], off offset:1024
	v_mfma_f32_32x32x16_bf16 v[16:31], v[128:131], v[132:135], v[16:31]
	s_mov_b32 m0, s57
	v_lshl_add_u64 v[148:149], v[66:67], 0, s[72:73]
	global_load_lds_dwordx4 v[148:149], off
	v_mfma_f32_32x32x16_bf16 v[0:15], v[128:131], v[136:139], v[0:15]
	global_load_lds_dwordx4 v[148:149], off offset:1024
	v_mfma_f32_32x32x16_bf16 v[184:199], v[128:131], v[140:143], v[184:199]
	v_mfma_f32_32x32x16_bf16 v[226:241], v[128:131], v[144:147], v[226:241]
	s_waitcnt vmcnt(6)
	s_waitcnt lgkmcnt(0)
	s_barrier
	ds_read_b128 v[110:113], v109
	ds_read_b128 v[132:135], v114 offset:8192
	v_mfma_f32_32x32x16_bf16 v[48:63], v[202:205], v[214:217], v[48:63]
	ds_read_b128 v[136:139], v114 offset:10240
	ds_read_b128 v[140:143], v114 offset:49152
	v_mfma_f32_32x32x16_bf16 v[32:47], v[202:205], v[244:247], v[32:47]
	ds_read_b128 v[144:147], v114 offset:51200
	ds_read_b128 v[128:131], v109 offset:2048
	v_mfma_f32_32x32x16_bf16 v[150:165], v[202:205], v[250:253], v[150:165]
	v_mfma_f32_32x32x16_bf16 v[166:181], v[202:205], v[74:77], v[166:181]
	ds_read_b128 v[202:205], v115
	v_mfma_f32_32x32x16_bf16 v[16:31], v[206:209], v[214:217], v[16:31]
	ds_read_b128 v[214:217], v119 offset:8192
	v_mfma_f32_32x32x16_bf16 v[0:15], v[206:209], v[244:247], v[0:15]
	ds_read_b128 v[244:247], v119 offset:10240
	v_mfma_f32_32x32x16_bf16 v[184:199], v[206:209], v[250:253], v[184:199]
	ds_read_b128 v[250:253], v119 offset:49152
	v_mfma_f32_32x32x16_bf16 v[226:241], v[206:209], v[74:77], v[226:241]
	ds_read_b128 v[206:209], v115 offset:2048
	ds_read_b128 v[74:77], v119 offset:51200
	s_waitcnt lgkmcnt(6)
	v_mfma_f32_32x32x16_bf16 v[48:63], v[110:113], v[132:135], v[48:63]
	s_mov_b32 m0, s52
	v_lshl_add_u64 v[64:65], v[64:65], 0, s[44:45]
	global_load_lds_dwordx4 v[64:65], off sc1
	v_mfma_f32_32x32x16_bf16 v[32:47], v[110:113], v[136:139], v[32:47]
	global_load_lds_dwordx4 v[64:65], off offset:1024 sc1
	v_mfma_f32_32x32x16_bf16 v[150:165], v[110:113], v[140:143], v[150:165]
	s_mov_b32 m0, s55
	v_lshl_add_u64 v[66:67], v[66:67], 0, s[44:45]
	global_load_lds_dwordx4 v[66:67], off
	v_mfma_f32_32x32x16_bf16 v[166:181], v[110:113], v[144:147], v[166:181]
	global_load_lds_dwordx4 v[66:67], off offset:1024
	v_mfma_f32_32x32x16_bf16 v[16:31], v[128:131], v[132:135], v[16:31]
	s_mov_b32 m0, s58
	v_lshl_add_u64 v[148:149], v[66:67], 0, s[72:73]
	global_load_lds_dwordx4 v[148:149], off
	v_mfma_f32_32x32x16_bf16 v[0:15], v[128:131], v[136:139], v[0:15]
	global_load_lds_dwordx4 v[148:149], off offset:1024
	v_mfma_f32_32x32x16_bf16 v[184:199], v[128:131], v[140:143], v[184:199]
	v_mfma_f32_32x32x16_bf16 v[226:241], v[128:131], v[144:147], v[226:241]
	s_waitcnt vmcnt(6)
	s_waitcnt lgkmcnt(0)
	s_barrier
	ds_read_b128 v[110:113], v109 offset:16384
	ds_read_b128 v[132:135], v114 offset:24576
	v_mfma_f32_32x32x16_bf16 v[48:63], v[202:205], v[214:217], v[48:63]
	ds_read_b128 v[136:139], v114 offset:26624
	ds_read_b128 v[140:143], v121 offset:40960
	v_mfma_f32_32x32x16_bf16 v[32:47], v[202:205], v[244:247], v[32:47]
	ds_read_b128 v[144:147], v121 offset:43008
	ds_read_b128 v[128:131], v109 offset:18432
	v_mfma_f32_32x32x16_bf16 v[150:165], v[202:205], v[250:253], v[150:165]
	v_mfma_f32_32x32x16_bf16 v[166:181], v[202:205], v[74:77], v[166:181]
	ds_read_b128 v[202:205], v115 offset:16384
	v_mfma_f32_32x32x16_bf16 v[16:31], v[206:209], v[214:217], v[16:31]
	ds_read_b128 v[214:217], v119 offset:24576
	v_mfma_f32_32x32x16_bf16 v[0:15], v[206:209], v[244:247], v[0:15]
	ds_read_b128 v[244:247], v119 offset:26624
	v_mfma_f32_32x32x16_bf16 v[184:199], v[206:209], v[250:253], v[184:199]
	ds_read_b128 v[250:253], v122 offset:40960
	v_mfma_f32_32x32x16_bf16 v[226:241], v[206:209], v[74:77], v[226:241]
	ds_read_b128 v[206:209], v115 offset:18432
	ds_read_b128 v[74:77], v122 offset:43008
	s_waitcnt lgkmcnt(6)
	v_mfma_f32_32x32x16_bf16 v[48:63], v[110:113], v[132:135], v[48:63]
	s_mov_b32 m0, s50
	v_lshl_add_u64 v[64:65], v[64:65], 0, s[44:45]
	global_load_lds_dwordx4 v[64:65], off sc1
	v_mfma_f32_32x32x16_bf16 v[32:47], v[110:113], v[136:139], v[32:47]
	global_load_lds_dwordx4 v[64:65], off offset:1024 sc1
	v_mfma_f32_32x32x16_bf16 v[150:165], v[110:113], v[140:143], v[150:165]
	s_mov_b32 m0, s53
	v_lshl_add_u64 v[66:67], v[66:67], 0, s[44:45]
	global_load_lds_dwordx4 v[66:67], off
	v_mfma_f32_32x32x16_bf16 v[166:181], v[110:113], v[144:147], v[166:181]
	global_load_lds_dwordx4 v[66:67], off offset:1024
	v_mfma_f32_32x32x16_bf16 v[16:31], v[128:131], v[132:135], v[16:31]
	s_mov_b32 m0, s56
	v_lshl_add_u64 v[148:149], v[66:67], 0, s[72:73]
	global_load_lds_dwordx4 v[148:149], off
	v_mfma_f32_32x32x16_bf16 v[0:15], v[128:131], v[136:139], v[0:15]
	global_load_lds_dwordx4 v[148:149], off offset:1024
	v_mfma_f32_32x32x16_bf16 v[184:199], v[128:131], v[140:143], v[184:199]
	v_mfma_f32_32x32x16_bf16 v[226:241], v[128:131], v[144:147], v[226:241]
	s_waitcnt vmcnt(6)
	s_waitcnt lgkmcnt(0)
	s_barrier
	ds_read_b128 v[110:113], v109 offset:32768
	ds_read_b128 v[132:135], v114 offset:40960
	v_mfma_f32_32x32x16_bf16 v[48:63], v[202:205], v[214:217], v[48:63]
	ds_read_b128 v[136:139], v114 offset:43008
	ds_read_b128 v[140:143], v121 offset:57344
	v_mfma_f32_32x32x16_bf16 v[32:47], v[202:205], v[244:247], v[32:47]
	ds_read_b128 v[144:147], v121 offset:59392
	ds_read_b128 v[128:131], v109 offset:34816
	v_mfma_f32_32x32x16_bf16 v[150:165], v[202:205], v[250:253], v[150:165]
	v_mfma_f32_32x32x16_bf16 v[166:181], v[202:205], v[74:77], v[166:181]
	ds_read_b128 v[202:205], v115 offset:32768
	v_mfma_f32_32x32x16_bf16 v[16:31], v[206:209], v[214:217], v[16:31]
	ds_read_b128 v[214:217], v119 offset:40960
	v_mfma_f32_32x32x16_bf16 v[0:15], v[206:209], v[244:247], v[0:15]
	ds_read_b128 v[244:247], v119 offset:43008
	v_mfma_f32_32x32x16_bf16 v[184:199], v[206:209], v[250:253], v[184:199]
	ds_read_b128 v[250:253], v122 offset:57344
	v_mfma_f32_32x32x16_bf16 v[226:241], v[206:209], v[74:77], v[226:241]
	ds_read_b128 v[206:209], v115 offset:34816
	ds_read_b128 v[74:77], v122 offset:59392
	s_waitcnt lgkmcnt(6)
	v_mfma_f32_32x32x16_bf16 v[48:63], v[110:113], v[132:135], v[48:63]
	s_mov_b32 m0, s51
	v_lshl_add_u64 v[64:65], v[64:65], 0, s[44:45]
	global_load_lds_dwordx4 v[64:65], off sc1
	v_mfma_f32_32x32x16_bf16 v[32:47], v[110:113], v[136:139], v[32:47]
	global_load_lds_dwordx4 v[64:65], off offset:1024 sc1
	v_mfma_f32_32x32x16_bf16 v[150:165], v[110:113], v[140:143], v[150:165]
	s_mov_b32 m0, s54
	v_lshl_add_u64 v[66:67], v[66:67], 0, s[44:45]
	global_load_lds_dwordx4 v[66:67], off
	v_mfma_f32_32x32x16_bf16 v[166:181], v[110:113], v[144:147], v[166:181]
	global_load_lds_dwordx4 v[66:67], off offset:1024
	v_mfma_f32_32x32x16_bf16 v[16:31], v[128:131], v[132:135], v[16:31]
	s_mov_b32 m0, s57
	v_lshl_add_u64 v[148:149], v[66:67], 0, s[72:73]
	global_load_lds_dwordx4 v[148:149], off
	v_mfma_f32_32x32x16_bf16 v[0:15], v[128:131], v[136:139], v[0:15]
	global_load_lds_dwordx4 v[148:149], off offset:1024
	v_mfma_f32_32x32x16_bf16 v[184:199], v[128:131], v[140:143], v[184:199]
	v_mfma_f32_32x32x16_bf16 v[226:241], v[128:131], v[144:147], v[226:241]
	s_waitcnt vmcnt(6)
	s_waitcnt lgkmcnt(0)
	s_barrier
	ds_read_b128 v[110:113], v109
	ds_read_b128 v[132:135], v114 offset:8192
	v_mfma_f32_32x32x16_bf16 v[48:63], v[202:205], v[214:217], v[48:63]
	ds_read_b128 v[136:139], v114 offset:10240
	ds_read_b128 v[140:143], v114 offset:49152
	v_mfma_f32_32x32x16_bf16 v[32:47], v[202:205], v[244:247], v[32:47]
	ds_read_b128 v[144:147], v114 offset:51200
	ds_read_b128 v[128:131], v109 offset:2048
	v_mfma_f32_32x32x16_bf16 v[150:165], v[202:205], v[250:253], v[150:165]
	v_mfma_f32_32x32x16_bf16 v[166:181], v[202:205], v[74:77], v[166:181]
	ds_read_b128 v[202:205], v115
	v_mfma_f32_32x32x16_bf16 v[16:31], v[206:209], v[214:217], v[16:31]
	ds_read_b128 v[214:217], v119 offset:8192
	v_mfma_f32_32x32x16_bf16 v[0:15], v[206:209], v[244:247], v[0:15]
	ds_read_b128 v[244:247], v119 offset:10240
	v_mfma_f32_32x32x16_bf16 v[184:199], v[206:209], v[250:253], v[184:199]
	ds_read_b128 v[250:253], v119 offset:49152
	v_mfma_f32_32x32x16_bf16 v[226:241], v[206:209], v[74:77], v[226:241]
	ds_read_b128 v[206:209], v115 offset:2048
	ds_read_b128 v[74:77], v119 offset:51200
	s_waitcnt lgkmcnt(6)
	v_mfma_f32_32x32x16_bf16 v[48:63], v[110:113], v[132:135], v[48:63]
	s_mov_b32 m0, s52
	v_lshl_add_u64 v[64:65], v[64:65], 0, s[44:45]
	global_load_lds_dwordx4 v[64:65], off sc1
	v_mfma_f32_32x32x16_bf16 v[32:47], v[110:113], v[136:139], v[32:47]
	global_load_lds_dwordx4 v[64:65], off offset:1024 sc1
	v_mfma_f32_32x32x16_bf16 v[150:165], v[110:113], v[140:143], v[150:165]
	s_mov_b32 m0, s55
	v_lshl_add_u64 v[66:67], v[66:67], 0, s[44:45]
	global_load_lds_dwordx4 v[66:67], off
	v_mfma_f32_32x32x16_bf16 v[166:181], v[110:113], v[144:147], v[166:181]
	global_load_lds_dwordx4 v[66:67], off offset:1024
	v_mfma_f32_32x32x16_bf16 v[16:31], v[128:131], v[132:135], v[16:31]
	s_mov_b32 m0, s58
	v_lshl_add_u64 v[148:149], v[66:67], 0, s[72:73]
	global_load_lds_dwordx4 v[148:149], off
	v_mfma_f32_32x32x16_bf16 v[0:15], v[128:131], v[136:139], v[0:15]
	global_load_lds_dwordx4 v[148:149], off offset:1024
	v_mfma_f32_32x32x16_bf16 v[184:199], v[128:131], v[140:143], v[184:199]
	v_mfma_f32_32x32x16_bf16 v[226:241], v[128:131], v[144:147], v[226:241]
	s_waitcnt vmcnt(6)
	s_waitcnt lgkmcnt(0)
	s_barrier
	ds_read_b128 v[110:113], v109 offset:16384
	ds_read_b128 v[132:135], v114 offset:24576
	v_mfma_f32_32x32x16_bf16 v[48:63], v[202:205], v[214:217], v[48:63]
	ds_read_b128 v[136:139], v114 offset:26624
	ds_read_b128 v[140:143], v121 offset:40960
	v_mfma_f32_32x32x16_bf16 v[32:47], v[202:205], v[244:247], v[32:47]
	ds_read_b128 v[144:147], v121 offset:43008
	ds_read_b128 v[128:131], v109 offset:18432
	v_mfma_f32_32x32x16_bf16 v[150:165], v[202:205], v[250:253], v[150:165]
	v_mfma_f32_32x32x16_bf16 v[166:181], v[202:205], v[74:77], v[166:181]
	ds_read_b128 v[202:205], v115 offset:16384
	v_mfma_f32_32x32x16_bf16 v[16:31], v[206:209], v[214:217], v[16:31]
	ds_read_b128 v[214:217], v119 offset:24576
	v_mfma_f32_32x32x16_bf16 v[0:15], v[206:209], v[244:247], v[0:15]
	ds_read_b128 v[244:247], v119 offset:26624
	v_mfma_f32_32x32x16_bf16 v[184:199], v[206:209], v[250:253], v[184:199]
	ds_read_b128 v[250:253], v122 offset:40960
	v_mfma_f32_32x32x16_bf16 v[226:241], v[206:209], v[74:77], v[226:241]
	ds_read_b128 v[206:209], v115 offset:18432
	ds_read_b128 v[74:77], v122 offset:43008
	s_waitcnt lgkmcnt(6)
	v_mfma_f32_32x32x16_bf16 v[48:63], v[110:113], v[132:135], v[48:63]
	s_mov_b32 m0, s50
	v_lshl_add_u64 v[64:65], v[64:65], 0, s[44:45]
	global_load_lds_dwordx4 v[64:65], off sc1
	v_mfma_f32_32x32x16_bf16 v[32:47], v[110:113], v[136:139], v[32:47]
	global_load_lds_dwordx4 v[64:65], off offset:1024 sc1
	v_mfma_f32_32x32x16_bf16 v[150:165], v[110:113], v[140:143], v[150:165]
	s_mov_b32 m0, s53
	v_lshl_add_u64 v[66:67], v[66:67], 0, s[44:45]
	global_load_lds_dwordx4 v[66:67], off
	v_mfma_f32_32x32x16_bf16 v[166:181], v[110:113], v[144:147], v[166:181]
	global_load_lds_dwordx4 v[66:67], off offset:1024
	v_mfma_f32_32x32x16_bf16 v[16:31], v[128:131], v[132:135], v[16:31]
	s_mov_b32 m0, s56
	v_lshl_add_u64 v[148:149], v[66:67], 0, s[72:73]
	global_load_lds_dwordx4 v[148:149], off
	v_mfma_f32_32x32x16_bf16 v[0:15], v[128:131], v[136:139], v[0:15]
	global_load_lds_dwordx4 v[148:149], off offset:1024
	v_mfma_f32_32x32x16_bf16 v[184:199], v[128:131], v[140:143], v[184:199]
	v_mfma_f32_32x32x16_bf16 v[226:241], v[128:131], v[144:147], v[226:241]
	s_waitcnt vmcnt(6)
	s_waitcnt lgkmcnt(0)
	s_barrier
	ds_read_b128 v[110:113], v109 offset:32768
	ds_read_b128 v[132:135], v114 offset:40960
	v_mfma_f32_32x32x16_bf16 v[48:63], v[202:205], v[214:217], v[48:63]
	ds_read_b128 v[136:139], v114 offset:43008
	ds_read_b128 v[140:143], v121 offset:57344
	v_mfma_f32_32x32x16_bf16 v[32:47], v[202:205], v[244:247], v[32:47]
	ds_read_b128 v[144:147], v121 offset:59392
	ds_read_b128 v[128:131], v109 offset:34816
	v_mfma_f32_32x32x16_bf16 v[150:165], v[202:205], v[250:253], v[150:165]
	v_mfma_f32_32x32x16_bf16 v[166:181], v[202:205], v[74:77], v[166:181]
	ds_read_b128 v[202:205], v115 offset:32768
	v_mfma_f32_32x32x16_bf16 v[16:31], v[206:209], v[214:217], v[16:31]
	ds_read_b128 v[214:217], v119 offset:40960
	v_mfma_f32_32x32x16_bf16 v[0:15], v[206:209], v[244:247], v[0:15]
	ds_read_b128 v[244:247], v119 offset:43008
	v_mfma_f32_32x32x16_bf16 v[184:199], v[206:209], v[250:253], v[184:199]
	ds_read_b128 v[250:253], v122 offset:57344
	v_mfma_f32_32x32x16_bf16 v[226:241], v[206:209], v[74:77], v[226:241]
	ds_read_b128 v[206:209], v115 offset:34816
	ds_read_b128 v[74:77], v122 offset:59392
	s_waitcnt lgkmcnt(6)
	v_mfma_f32_32x32x16_bf16 v[48:63], v[110:113], v[132:135], v[48:63]
	s_mov_b32 m0, s51
	v_lshl_add_u64 v[64:65], v[64:65], 0, s[44:45]
	global_load_lds_dwordx4 v[64:65], off sc1
	v_mfma_f32_32x32x16_bf16 v[32:47], v[110:113], v[136:139], v[32:47]
	global_load_lds_dwordx4 v[64:65], off offset:1024 sc1
	v_mfma_f32_32x32x16_bf16 v[150:165], v[110:113], v[140:143], v[150:165]
	s_mov_b32 m0, s54
	v_lshl_add_u64 v[66:67], v[66:67], 0, s[44:45]
	global_load_lds_dwordx4 v[66:67], off
	v_mfma_f32_32x32x16_bf16 v[166:181], v[110:113], v[144:147], v[166:181]
	global_load_lds_dwordx4 v[66:67], off offset:1024
	v_mfma_f32_32x32x16_bf16 v[16:31], v[128:131], v[132:135], v[16:31]
	s_mov_b32 m0, s57
	v_lshl_add_u64 v[148:149], v[66:67], 0, s[72:73]
	global_load_lds_dwordx4 v[148:149], off
	v_mfma_f32_32x32x16_bf16 v[0:15], v[128:131], v[136:139], v[0:15]
	global_load_lds_dwordx4 v[148:149], off offset:1024
	v_mfma_f32_32x32x16_bf16 v[184:199], v[128:131], v[140:143], v[184:199]
	v_mfma_f32_32x32x16_bf16 v[226:241], v[128:131], v[144:147], v[226:241]
	s_waitcnt vmcnt(6)
	s_waitcnt lgkmcnt(0)
	s_barrier
	ds_read_b128 v[110:113], v109
	ds_read_b128 v[132:135], v114 offset:8192
	v_mfma_f32_32x32x16_bf16 v[48:63], v[202:205], v[214:217], v[48:63]
	ds_read_b128 v[136:139], v114 offset:10240
	ds_read_b128 v[140:143], v114 offset:49152
	v_mfma_f32_32x32x16_bf16 v[32:47], v[202:205], v[244:247], v[32:47]
	ds_read_b128 v[144:147], v114 offset:51200
	ds_read_b128 v[128:131], v109 offset:2048
	v_mfma_f32_32x32x16_bf16 v[150:165], v[202:205], v[250:253], v[150:165]
	v_mfma_f32_32x32x16_bf16 v[166:181], v[202:205], v[74:77], v[166:181]
	ds_read_b128 v[202:205], v115
	v_mfma_f32_32x32x16_bf16 v[16:31], v[206:209], v[214:217], v[16:31]
	ds_read_b128 v[214:217], v119 offset:8192
	v_mfma_f32_32x32x16_bf16 v[0:15], v[206:209], v[244:247], v[0:15]
	ds_read_b128 v[244:247], v119 offset:10240
	v_mfma_f32_32x32x16_bf16 v[184:199], v[206:209], v[250:253], v[184:199]
	ds_read_b128 v[250:253], v119 offset:49152
	v_mfma_f32_32x32x16_bf16 v[226:241], v[206:209], v[74:77], v[226:241]
	ds_read_b128 v[206:209], v115 offset:2048
	ds_read_b128 v[74:77], v119 offset:51200
	s_waitcnt lgkmcnt(6)
	v_mfma_f32_32x32x16_bf16 v[48:63], v[110:113], v[132:135], v[48:63]
	s_mov_b32 m0, s52
	v_lshl_add_u64 v[64:65], v[64:65], 0, s[44:45]
	global_load_lds_dwordx4 v[64:65], off sc1
	v_mfma_f32_32x32x16_bf16 v[32:47], v[110:113], v[136:139], v[32:47]
	global_load_lds_dwordx4 v[64:65], off offset:1024 sc1
	v_mfma_f32_32x32x16_bf16 v[150:165], v[110:113], v[140:143], v[150:165]
	s_mov_b32 m0, s55
	v_lshl_add_u64 v[66:67], v[66:67], 0, s[44:45]
	global_load_lds_dwordx4 v[66:67], off
	v_mfma_f32_32x32x16_bf16 v[166:181], v[110:113], v[144:147], v[166:181]
	global_load_lds_dwordx4 v[66:67], off offset:1024
	v_mfma_f32_32x32x16_bf16 v[16:31], v[128:131], v[132:135], v[16:31]
	s_mov_b32 m0, s58
	v_lshl_add_u64 v[148:149], v[66:67], 0, s[72:73]
	global_load_lds_dwordx4 v[148:149], off
	v_mfma_f32_32x32x16_bf16 v[0:15], v[128:131], v[136:139], v[0:15]
	global_load_lds_dwordx4 v[148:149], off offset:1024
	v_mfma_f32_32x32x16_bf16 v[184:199], v[128:131], v[140:143], v[184:199]
	v_mfma_f32_32x32x16_bf16 v[226:241], v[128:131], v[144:147], v[226:241]
	s_waitcnt vmcnt(6)
	s_waitcnt lgkmcnt(0)
	s_barrier
	ds_read_b128 v[110:113], v109 offset:16384
	ds_read_b128 v[132:135], v114 offset:24576
	v_mfma_f32_32x32x16_bf16 v[48:63], v[202:205], v[214:217], v[48:63]
	ds_read_b128 v[136:139], v114 offset:26624
	ds_read_b128 v[140:143], v121 offset:40960
	v_mfma_f32_32x32x16_bf16 v[32:47], v[202:205], v[244:247], v[32:47]
	ds_read_b128 v[144:147], v121 offset:43008
	ds_read_b128 v[128:131], v109 offset:18432
	v_mfma_f32_32x32x16_bf16 v[150:165], v[202:205], v[250:253], v[150:165]
	v_mfma_f32_32x32x16_bf16 v[166:181], v[202:205], v[74:77], v[166:181]
	ds_read_b128 v[202:205], v115 offset:16384
	v_mfma_f32_32x32x16_bf16 v[16:31], v[206:209], v[214:217], v[16:31]
	ds_read_b128 v[214:217], v119 offset:24576
	v_mfma_f32_32x32x16_bf16 v[0:15], v[206:209], v[244:247], v[0:15]
	ds_read_b128 v[244:247], v119 offset:26624
	v_mfma_f32_32x32x16_bf16 v[184:199], v[206:209], v[250:253], v[184:199]
	ds_read_b128 v[250:253], v122 offset:40960
	v_mfma_f32_32x32x16_bf16 v[226:241], v[206:209], v[74:77], v[226:241]
	ds_read_b128 v[206:209], v115 offset:18432
	ds_read_b128 v[74:77], v122 offset:43008
	s_waitcnt lgkmcnt(6)
	v_mfma_f32_32x32x16_bf16 v[48:63], v[110:113], v[132:135], v[48:63]
	s_mov_b32 m0, s50
	v_lshl_add_u64 v[64:65], v[64:65], 0, s[44:45]
	global_load_lds_dwordx4 v[64:65], off sc1
	v_mfma_f32_32x32x16_bf16 v[32:47], v[110:113], v[136:139], v[32:47]
	global_load_lds_dwordx4 v[64:65], off offset:1024 sc1
	v_mfma_f32_32x32x16_bf16 v[150:165], v[110:113], v[140:143], v[150:165]
	s_mov_b32 m0, s53
	v_lshl_add_u64 v[66:67], v[66:67], 0, s[44:45]
	global_load_lds_dwordx4 v[66:67], off
	v_mfma_f32_32x32x16_bf16 v[166:181], v[110:113], v[144:147], v[166:181]
	global_load_lds_dwordx4 v[66:67], off offset:1024
	v_mfma_f32_32x32x16_bf16 v[16:31], v[128:131], v[132:135], v[16:31]
	s_mov_b32 m0, s56
	v_lshl_add_u64 v[148:149], v[66:67], 0, s[72:73]
	global_load_lds_dwordx4 v[148:149], off
	v_mfma_f32_32x32x16_bf16 v[0:15], v[128:131], v[136:139], v[0:15]
	global_load_lds_dwordx4 v[148:149], off offset:1024
	v_mfma_f32_32x32x16_bf16 v[184:199], v[128:131], v[140:143], v[184:199]
	v_mfma_f32_32x32x16_bf16 v[226:241], v[128:131], v[144:147], v[226:241]
	s_waitcnt vmcnt(6)
	s_waitcnt lgkmcnt(0)
	s_barrier
	ds_read_b128 v[110:113], v109 offset:32768
	ds_read_b128 v[132:135], v114 offset:40960
	v_mfma_f32_32x32x16_bf16 v[48:63], v[202:205], v[214:217], v[48:63]
	ds_read_b128 v[136:139], v114 offset:43008
	ds_read_b128 v[140:143], v121 offset:57344
	v_mfma_f32_32x32x16_bf16 v[32:47], v[202:205], v[244:247], v[32:47]
	ds_read_b128 v[144:147], v121 offset:59392
	ds_read_b128 v[128:131], v109 offset:34816
	v_mfma_f32_32x32x16_bf16 v[150:165], v[202:205], v[250:253], v[150:165]
	v_mfma_f32_32x32x16_bf16 v[166:181], v[202:205], v[74:77], v[166:181]
	ds_read_b128 v[202:205], v115 offset:32768
	v_mfma_f32_32x32x16_bf16 v[16:31], v[206:209], v[214:217], v[16:31]
	ds_read_b128 v[214:217], v119 offset:40960
	v_mfma_f32_32x32x16_bf16 v[0:15], v[206:209], v[244:247], v[0:15]
	ds_read_b128 v[244:247], v119 offset:43008
	v_mfma_f32_32x32x16_bf16 v[184:199], v[206:209], v[250:253], v[184:199]
	ds_read_b128 v[250:253], v122 offset:57344
	v_mfma_f32_32x32x16_bf16 v[226:241], v[206:209], v[74:77], v[226:241]
	ds_read_b128 v[206:209], v115 offset:34816
	ds_read_b128 v[74:77], v122 offset:59392
	s_waitcnt lgkmcnt(6)
	v_mfma_f32_32x32x16_bf16 v[48:63], v[110:113], v[132:135], v[48:63]
	s_mov_b32 m0, s51
	v_lshl_add_u64 v[64:65], v[64:65], 0, s[44:45]
	global_load_lds_dwordx4 v[64:65], off sc1
	v_mfma_f32_32x32x16_bf16 v[32:47], v[110:113], v[136:139], v[32:47]
	global_load_lds_dwordx4 v[64:65], off offset:1024 sc1
	v_mfma_f32_32x32x16_bf16 v[150:165], v[110:113], v[140:143], v[150:165]
	s_mov_b32 m0, s54
	v_lshl_add_u64 v[66:67], v[66:67], 0, s[44:45]
	global_load_lds_dwordx4 v[66:67], off
	v_mfma_f32_32x32x16_bf16 v[166:181], v[110:113], v[144:147], v[166:181]
	global_load_lds_dwordx4 v[66:67], off offset:1024
	v_mfma_f32_32x32x16_bf16 v[16:31], v[128:131], v[132:135], v[16:31]
	s_mov_b32 m0, s57
	v_lshl_add_u64 v[148:149], v[66:67], 0, s[72:73]
	global_load_lds_dwordx4 v[148:149], off
	v_mfma_f32_32x32x16_bf16 v[0:15], v[128:131], v[136:139], v[0:15]
	global_load_lds_dwordx4 v[148:149], off offset:1024
	v_mfma_f32_32x32x16_bf16 v[184:199], v[128:131], v[140:143], v[184:199]
	v_mfma_f32_32x32x16_bf16 v[226:241], v[128:131], v[144:147], v[226:241]
	s_waitcnt vmcnt(6)
	s_waitcnt lgkmcnt(0)
	s_barrier
	ds_read_b128 v[110:113], v109
	ds_read_b128 v[132:135], v114 offset:8192
	v_mfma_f32_32x32x16_bf16 v[48:63], v[202:205], v[214:217], v[48:63]
	ds_read_b128 v[136:139], v114 offset:10240
	ds_read_b128 v[140:143], v114 offset:49152
	v_mfma_f32_32x32x16_bf16 v[32:47], v[202:205], v[244:247], v[32:47]
	ds_read_b128 v[144:147], v114 offset:51200
	ds_read_b128 v[128:131], v109 offset:2048
	v_mfma_f32_32x32x16_bf16 v[150:165], v[202:205], v[250:253], v[150:165]
	v_mfma_f32_32x32x16_bf16 v[166:181], v[202:205], v[74:77], v[166:181]
	ds_read_b128 v[202:205], v115
	v_mfma_f32_32x32x16_bf16 v[16:31], v[206:209], v[214:217], v[16:31]
	ds_read_b128 v[214:217], v119 offset:8192
	v_mfma_f32_32x32x16_bf16 v[0:15], v[206:209], v[244:247], v[0:15]
	ds_read_b128 v[244:247], v119 offset:10240
	v_mfma_f32_32x32x16_bf16 v[184:199], v[206:209], v[250:253], v[184:199]
	ds_read_b128 v[250:253], v119 offset:49152
	v_mfma_f32_32x32x16_bf16 v[226:241], v[206:209], v[74:77], v[226:241]
	ds_read_b128 v[206:209], v115 offset:2048
	ds_read_b128 v[74:77], v119 offset:51200
	s_waitcnt lgkmcnt(6)
	v_mfma_f32_32x32x16_bf16 v[48:63], v[110:113], v[132:135], v[48:63]
	s_mov_b32 m0, s52
	v_lshl_add_u64 v[64:65], v[64:65], 0, s[44:45]
	global_load_lds_dwordx4 v[64:65], off sc1
	v_mfma_f32_32x32x16_bf16 v[32:47], v[110:113], v[136:139], v[32:47]
	global_load_lds_dwordx4 v[64:65], off offset:1024 sc1
	v_mfma_f32_32x32x16_bf16 v[150:165], v[110:113], v[140:143], v[150:165]
	s_mov_b32 m0, s55
	v_lshl_add_u64 v[66:67], v[66:67], 0, s[44:45]
	global_load_lds_dwordx4 v[66:67], off
	v_mfma_f32_32x32x16_bf16 v[166:181], v[110:113], v[144:147], v[166:181]
	global_load_lds_dwordx4 v[66:67], off offset:1024
	v_mfma_f32_32x32x16_bf16 v[16:31], v[128:131], v[132:135], v[16:31]
	s_mov_b32 m0, s58
	v_lshl_add_u64 v[148:149], v[66:67], 0, s[72:73]
	global_load_lds_dwordx4 v[148:149], off
	v_mfma_f32_32x32x16_bf16 v[0:15], v[128:131], v[136:139], v[0:15]
	global_load_lds_dwordx4 v[148:149], off offset:1024
	v_mfma_f32_32x32x16_bf16 v[184:199], v[128:131], v[140:143], v[184:199]
	v_mfma_f32_32x32x16_bf16 v[226:241], v[128:131], v[144:147], v[226:241]
	s_waitcnt vmcnt(6)
	s_waitcnt lgkmcnt(0)
	s_barrier
	ds_read_b128 v[110:113], v109 offset:16384
	ds_read_b128 v[132:135], v114 offset:24576
	v_mfma_f32_32x32x16_bf16 v[48:63], v[202:205], v[214:217], v[48:63]
	ds_read_b128 v[136:139], v114 offset:26624
	ds_read_b128 v[140:143], v121 offset:40960
	v_mfma_f32_32x32x16_bf16 v[32:47], v[202:205], v[244:247], v[32:47]
	ds_read_b128 v[144:147], v121 offset:43008
	ds_read_b128 v[128:131], v109 offset:18432
	v_mfma_f32_32x32x16_bf16 v[150:165], v[202:205], v[250:253], v[150:165]
	v_mfma_f32_32x32x16_bf16 v[166:181], v[202:205], v[74:77], v[166:181]
	ds_read_b128 v[202:205], v115 offset:16384
	v_mfma_f32_32x32x16_bf16 v[16:31], v[206:209], v[214:217], v[16:31]
	ds_read_b128 v[214:217], v119 offset:24576
	v_mfma_f32_32x32x16_bf16 v[0:15], v[206:209], v[244:247], v[0:15]
	ds_read_b128 v[244:247], v119 offset:26624
	v_mfma_f32_32x32x16_bf16 v[184:199], v[206:209], v[250:253], v[184:199]
	ds_read_b128 v[250:253], v122 offset:40960
	v_mfma_f32_32x32x16_bf16 v[226:241], v[206:209], v[74:77], v[226:241]
	ds_read_b128 v[206:209], v115 offset:18432
	ds_read_b128 v[74:77], v122 offset:43008
	s_waitcnt lgkmcnt(6)
	v_mfma_f32_32x32x16_bf16 v[48:63], v[110:113], v[132:135], v[48:63]
	s_mov_b32 m0, s50
	v_lshl_add_u64 v[64:65], v[64:65], 0, s[44:45]
	global_load_lds_dwordx4 v[64:65], off sc1
	v_mfma_f32_32x32x16_bf16 v[32:47], v[110:113], v[136:139], v[32:47]
	global_load_lds_dwordx4 v[64:65], off offset:1024 sc1
	v_mfma_f32_32x32x16_bf16 v[150:165], v[110:113], v[140:143], v[150:165]
	s_mov_b32 m0, s53
	v_lshl_add_u64 v[66:67], v[66:67], 0, s[44:45]
	global_load_lds_dwordx4 v[66:67], off
	v_mfma_f32_32x32x16_bf16 v[166:181], v[110:113], v[144:147], v[166:181]
	global_load_lds_dwordx4 v[66:67], off offset:1024
	v_mfma_f32_32x32x16_bf16 v[16:31], v[128:131], v[132:135], v[16:31]
	s_mov_b32 m0, s56
	v_lshl_add_u64 v[148:149], v[66:67], 0, s[72:73]
	global_load_lds_dwordx4 v[148:149], off
	v_mfma_f32_32x32x16_bf16 v[0:15], v[128:131], v[136:139], v[0:15]
	global_load_lds_dwordx4 v[148:149], off offset:1024
	v_mfma_f32_32x32x16_bf16 v[184:199], v[128:131], v[140:143], v[184:199]
	v_mfma_f32_32x32x16_bf16 v[226:241], v[128:131], v[144:147], v[226:241]
	s_waitcnt vmcnt(6)
	s_waitcnt lgkmcnt(0)
	s_barrier
	ds_read_b128 v[110:113], v109 offset:32768
	ds_read_b128 v[132:135], v114 offset:40960
	v_mfma_f32_32x32x16_bf16 v[48:63], v[202:205], v[214:217], v[48:63]
	ds_read_b128 v[136:139], v114 offset:43008
	ds_read_b128 v[140:143], v121 offset:57344
	v_mfma_f32_32x32x16_bf16 v[32:47], v[202:205], v[244:247], v[32:47]
	ds_read_b128 v[144:147], v121 offset:59392
	ds_read_b128 v[128:131], v109 offset:34816
	v_mfma_f32_32x32x16_bf16 v[150:165], v[202:205], v[250:253], v[150:165]
	v_mfma_f32_32x32x16_bf16 v[166:181], v[202:205], v[74:77], v[166:181]
	ds_read_b128 v[202:205], v115 offset:32768
	v_mfma_f32_32x32x16_bf16 v[16:31], v[206:209], v[214:217], v[16:31]
	ds_read_b128 v[214:217], v119 offset:40960
	v_mfma_f32_32x32x16_bf16 v[0:15], v[206:209], v[244:247], v[0:15]
	ds_read_b128 v[244:247], v119 offset:43008
	v_mfma_f32_32x32x16_bf16 v[184:199], v[206:209], v[250:253], v[184:199]
	ds_read_b128 v[250:253], v122 offset:57344
	v_mfma_f32_32x32x16_bf16 v[226:241], v[206:209], v[74:77], v[226:241]
	ds_read_b128 v[206:209], v115 offset:34816
	ds_read_b128 v[74:77], v122 offset:59392
	s_waitcnt lgkmcnt(6)
	v_mfma_f32_32x32x16_bf16 v[48:63], v[110:113], v[132:135], v[48:63]
	s_mov_b32 m0, s51
	v_lshl_add_u64 v[64:65], v[64:65], 0, s[44:45]
	global_load_lds_dwordx4 v[64:65], off sc1
	v_mfma_f32_32x32x16_bf16 v[32:47], v[110:113], v[136:139], v[32:47]
	global_load_lds_dwordx4 v[64:65], off offset:1024 sc1
	v_mfma_f32_32x32x16_bf16 v[150:165], v[110:113], v[140:143], v[150:165]
	s_mov_b32 m0, s54
	v_lshl_add_u64 v[66:67], v[66:67], 0, s[44:45]
	global_load_lds_dwordx4 v[66:67], off
	v_mfma_f32_32x32x16_bf16 v[166:181], v[110:113], v[144:147], v[166:181]
	global_load_lds_dwordx4 v[66:67], off offset:1024
	v_mfma_f32_32x32x16_bf16 v[16:31], v[128:131], v[132:135], v[16:31]
	s_mov_b32 m0, s57
	v_lshl_add_u64 v[148:149], v[66:67], 0, s[72:73]
	global_load_lds_dwordx4 v[148:149], off
	v_mfma_f32_32x32x16_bf16 v[0:15], v[128:131], v[136:139], v[0:15]
	global_load_lds_dwordx4 v[148:149], off offset:1024
	v_mfma_f32_32x32x16_bf16 v[184:199], v[128:131], v[140:143], v[184:199]
	v_mfma_f32_32x32x16_bf16 v[226:241], v[128:131], v[144:147], v[226:241]
	s_waitcnt vmcnt(6)
	s_waitcnt lgkmcnt(0)
	s_barrier
	ds_read_b128 v[110:113], v109
	ds_read_b128 v[132:135], v114 offset:8192
	v_mfma_f32_32x32x16_bf16 v[48:63], v[202:205], v[214:217], v[48:63]
	ds_read_b128 v[136:139], v114 offset:10240
	ds_read_b128 v[140:143], v114 offset:49152
	v_mfma_f32_32x32x16_bf16 v[32:47], v[202:205], v[244:247], v[32:47]
	ds_read_b128 v[144:147], v114 offset:51200
	ds_read_b128 v[128:131], v109 offset:2048
	v_mfma_f32_32x32x16_bf16 v[150:165], v[202:205], v[250:253], v[150:165]
	v_mfma_f32_32x32x16_bf16 v[166:181], v[202:205], v[74:77], v[166:181]
	ds_read_b128 v[202:205], v115
	v_mfma_f32_32x32x16_bf16 v[16:31], v[206:209], v[214:217], v[16:31]
	ds_read_b128 v[214:217], v119 offset:8192
	v_mfma_f32_32x32x16_bf16 v[0:15], v[206:209], v[244:247], v[0:15]
	ds_read_b128 v[244:247], v119 offset:10240
	v_mfma_f32_32x32x16_bf16 v[184:199], v[206:209], v[250:253], v[184:199]
	ds_read_b128 v[250:253], v119 offset:49152
	v_mfma_f32_32x32x16_bf16 v[226:241], v[206:209], v[74:77], v[226:241]
	ds_read_b128 v[206:209], v115 offset:2048
	ds_read_b128 v[74:77], v119 offset:51200
	s_waitcnt lgkmcnt(6)
	v_mfma_f32_32x32x16_bf16 v[48:63], v[110:113], v[132:135], v[48:63]
	s_mov_b32 m0, s52
	v_lshl_add_u64 v[64:65], v[64:65], 0, s[44:45]
	global_load_lds_dwordx4 v[64:65], off sc1
	v_mfma_f32_32x32x16_bf16 v[32:47], v[110:113], v[136:139], v[32:47]
	global_load_lds_dwordx4 v[64:65], off offset:1024 sc1
	v_mfma_f32_32x32x16_bf16 v[150:165], v[110:113], v[140:143], v[150:165]
	s_mov_b32 m0, s55
	v_lshl_add_u64 v[66:67], v[66:67], 0, s[44:45]
	global_load_lds_dwordx4 v[66:67], off
	v_mfma_f32_32x32x16_bf16 v[166:181], v[110:113], v[144:147], v[166:181]
	global_load_lds_dwordx4 v[66:67], off offset:1024
	v_mfma_f32_32x32x16_bf16 v[16:31], v[128:131], v[132:135], v[16:31]
	s_mov_b32 m0, s58
	v_lshl_add_u64 v[148:149], v[66:67], 0, s[72:73]
	global_load_lds_dwordx4 v[148:149], off
	v_mfma_f32_32x32x16_bf16 v[0:15], v[128:131], v[136:139], v[0:15]
	global_load_lds_dwordx4 v[148:149], off offset:1024
	v_mfma_f32_32x32x16_bf16 v[184:199], v[128:131], v[140:143], v[184:199]
	v_mfma_f32_32x32x16_bf16 v[226:241], v[128:131], v[144:147], v[226:241]
	s_waitcnt vmcnt(6)
	s_waitcnt lgkmcnt(0)
	s_barrier
	ds_read_b128 v[110:113], v109 offset:16384
	ds_read_b128 v[132:135], v114 offset:24576
	v_mfma_f32_32x32x16_bf16 v[48:63], v[202:205], v[214:217], v[48:63]
	ds_read_b128 v[136:139], v114 offset:26624
	ds_read_b128 v[140:143], v121 offset:40960
	v_mfma_f32_32x32x16_bf16 v[32:47], v[202:205], v[244:247], v[32:47]
	ds_read_b128 v[144:147], v121 offset:43008
	ds_read_b128 v[128:131], v109 offset:18432
	v_mfma_f32_32x32x16_bf16 v[150:165], v[202:205], v[250:253], v[150:165]
	v_mfma_f32_32x32x16_bf16 v[166:181], v[202:205], v[74:77], v[166:181]
	ds_read_b128 v[202:205], v115 offset:16384
	v_mfma_f32_32x32x16_bf16 v[16:31], v[206:209], v[214:217], v[16:31]
	ds_read_b128 v[214:217], v119 offset:24576
	v_mfma_f32_32x32x16_bf16 v[0:15], v[206:209], v[244:247], v[0:15]
	ds_read_b128 v[244:247], v119 offset:26624
	v_mfma_f32_32x32x16_bf16 v[184:199], v[206:209], v[250:253], v[184:199]
	ds_read_b128 v[250:253], v122 offset:40960
	v_mfma_f32_32x32x16_bf16 v[226:241], v[206:209], v[74:77], v[226:241]
	ds_read_b128 v[206:209], v115 offset:18432
	ds_read_b128 v[74:77], v122 offset:43008
	s_waitcnt lgkmcnt(6)
	v_mfma_f32_32x32x16_bf16 v[48:63], v[110:113], v[132:135], v[48:63]
	s_mov_b32 m0, s50
	v_lshl_add_u64 v[64:65], v[64:65], 0, s[44:45]
	global_load_lds_dwordx4 v[64:65], off sc1
	v_mfma_f32_32x32x16_bf16 v[32:47], v[110:113], v[136:139], v[32:47]
	global_load_lds_dwordx4 v[64:65], off offset:1024 sc1
	v_mfma_f32_32x32x16_bf16 v[150:165], v[110:113], v[140:143], v[150:165]
	s_mov_b32 m0, s53
	v_lshl_add_u64 v[66:67], v[66:67], 0, s[44:45]
	global_load_lds_dwordx4 v[66:67], off
	v_mfma_f32_32x32x16_bf16 v[166:181], v[110:113], v[144:147], v[166:181]
	global_load_lds_dwordx4 v[66:67], off offset:1024
	v_mfma_f32_32x32x16_bf16 v[16:31], v[128:131], v[132:135], v[16:31]
	s_mov_b32 m0, s56
	v_lshl_add_u64 v[148:149], v[66:67], 0, s[72:73]
	global_load_lds_dwordx4 v[148:149], off
	v_mfma_f32_32x32x16_bf16 v[0:15], v[128:131], v[136:139], v[0:15]
	global_load_lds_dwordx4 v[148:149], off offset:1024
	v_mfma_f32_32x32x16_bf16 v[184:199], v[128:131], v[140:143], v[184:199]
	v_mfma_f32_32x32x16_bf16 v[226:241], v[128:131], v[144:147], v[226:241]
	s_waitcnt vmcnt(6)
	s_waitcnt lgkmcnt(0)
	s_barrier
	ds_read_b128 v[110:113], v109 offset:32768
	ds_read_b128 v[132:135], v114 offset:40960
	v_mfma_f32_32x32x16_bf16 v[48:63], v[202:205], v[214:217], v[48:63]
	ds_read_b128 v[136:139], v114 offset:43008
	ds_read_b128 v[140:143], v121 offset:57344
	v_mfma_f32_32x32x16_bf16 v[32:47], v[202:205], v[244:247], v[32:47]
	ds_read_b128 v[144:147], v121 offset:59392
	ds_read_b128 v[128:131], v109 offset:34816
	v_mfma_f32_32x32x16_bf16 v[150:165], v[202:205], v[250:253], v[150:165]
	v_mfma_f32_32x32x16_bf16 v[166:181], v[202:205], v[74:77], v[166:181]
	ds_read_b128 v[202:205], v115 offset:32768
	v_mfma_f32_32x32x16_bf16 v[16:31], v[206:209], v[214:217], v[16:31]
	ds_read_b128 v[214:217], v119 offset:40960
	v_mfma_f32_32x32x16_bf16 v[0:15], v[206:209], v[244:247], v[0:15]
	ds_read_b128 v[244:247], v119 offset:43008
	v_mfma_f32_32x32x16_bf16 v[184:199], v[206:209], v[250:253], v[184:199]
	ds_read_b128 v[250:253], v122 offset:57344
	v_mfma_f32_32x32x16_bf16 v[226:241], v[206:209], v[74:77], v[226:241]
	ds_read_b128 v[206:209], v115 offset:34816
	ds_read_b128 v[74:77], v122 offset:59392
	s_waitcnt lgkmcnt(6)
	v_mfma_f32_32x32x16_bf16 v[48:63], v[110:113], v[132:135], v[48:63]
	s_mov_b32 m0, s51
	v_lshl_add_u64 v[64:65], v[64:65], 0, s[44:45]
	global_load_lds_dwordx4 v[64:65], off sc1
	v_mfma_f32_32x32x16_bf16 v[32:47], v[110:113], v[136:139], v[32:47]
	global_load_lds_dwordx4 v[64:65], off offset:1024 sc1
	v_mfma_f32_32x32x16_bf16 v[150:165], v[110:113], v[140:143], v[150:165]
	s_mov_b32 m0, s54
	v_lshl_add_u64 v[66:67], v[66:67], 0, s[44:45]
	global_load_lds_dwordx4 v[66:67], off
	v_mfma_f32_32x32x16_bf16 v[166:181], v[110:113], v[144:147], v[166:181]
	global_load_lds_dwordx4 v[66:67], off offset:1024
	v_mfma_f32_32x32x16_bf16 v[16:31], v[128:131], v[132:135], v[16:31]
	s_mov_b32 m0, s57
	v_lshl_add_u64 v[148:149], v[66:67], 0, s[72:73]
	global_load_lds_dwordx4 v[148:149], off
	v_mfma_f32_32x32x16_bf16 v[0:15], v[128:131], v[136:139], v[0:15]
	global_load_lds_dwordx4 v[148:149], off offset:1024
	v_mfma_f32_32x32x16_bf16 v[184:199], v[128:131], v[140:143], v[184:199]
	v_mfma_f32_32x32x16_bf16 v[226:241], v[128:131], v[144:147], v[226:241]
	s_waitcnt vmcnt(6)
	s_waitcnt lgkmcnt(0)
	s_barrier
	ds_read_b128 v[110:113], v109
	ds_read_b128 v[132:135], v114 offset:8192
	v_mfma_f32_32x32x16_bf16 v[48:63], v[202:205], v[214:217], v[48:63]
	ds_read_b128 v[136:139], v114 offset:10240
	ds_read_b128 v[140:143], v114 offset:49152
	v_mfma_f32_32x32x16_bf16 v[32:47], v[202:205], v[244:247], v[32:47]
	ds_read_b128 v[144:147], v114 offset:51200
	ds_read_b128 v[128:131], v109 offset:2048
	v_mfma_f32_32x32x16_bf16 v[150:165], v[202:205], v[250:253], v[150:165]
	v_mfma_f32_32x32x16_bf16 v[166:181], v[202:205], v[74:77], v[166:181]
	ds_read_b128 v[202:205], v115
	v_mfma_f32_32x32x16_bf16 v[16:31], v[206:209], v[214:217], v[16:31]
	ds_read_b128 v[214:217], v119 offset:8192
	v_mfma_f32_32x32x16_bf16 v[0:15], v[206:209], v[244:247], v[0:15]
	ds_read_b128 v[244:247], v119 offset:10240
	v_mfma_f32_32x32x16_bf16 v[184:199], v[206:209], v[250:253], v[184:199]
	ds_read_b128 v[250:253], v119 offset:49152
	v_mfma_f32_32x32x16_bf16 v[226:241], v[206:209], v[74:77], v[226:241]
	ds_read_b128 v[206:209], v115 offset:2048
	ds_read_b128 v[74:77], v119 offset:51200
	s_waitcnt lgkmcnt(6)
	v_mfma_f32_32x32x16_bf16 v[48:63], v[110:113], v[132:135], v[48:63]
	s_mov_b32 m0, s52
	v_lshl_add_u64 v[64:65], v[64:65], 0, s[44:45]
	global_load_lds_dwordx4 v[64:65], off sc1
	v_mfma_f32_32x32x16_bf16 v[32:47], v[110:113], v[136:139], v[32:47]
	global_load_lds_dwordx4 v[64:65], off offset:1024 sc1
	v_mfma_f32_32x32x16_bf16 v[150:165], v[110:113], v[140:143], v[150:165]
	s_mov_b32 m0, s55
	v_lshl_add_u64 v[66:67], v[66:67], 0, s[44:45]
	global_load_lds_dwordx4 v[66:67], off
	v_mfma_f32_32x32x16_bf16 v[166:181], v[110:113], v[144:147], v[166:181]
	global_load_lds_dwordx4 v[66:67], off offset:1024
	v_mfma_f32_32x32x16_bf16 v[16:31], v[128:131], v[132:135], v[16:31]
	s_mov_b32 m0, s58
	v_lshl_add_u64 v[148:149], v[66:67], 0, s[72:73]
	global_load_lds_dwordx4 v[148:149], off
	v_mfma_f32_32x32x16_bf16 v[0:15], v[128:131], v[136:139], v[0:15]
	global_load_lds_dwordx4 v[148:149], off offset:1024
	v_mfma_f32_32x32x16_bf16 v[184:199], v[128:131], v[140:143], v[184:199]
	v_mfma_f32_32x32x16_bf16 v[226:241], v[128:131], v[144:147], v[226:241]
	s_waitcnt vmcnt(6)
	s_waitcnt lgkmcnt(0)
	s_barrier
	ds_read_b128 v[110:113], v109 offset:16384
	ds_read_b128 v[132:135], v114 offset:24576
	v_mfma_f32_32x32x16_bf16 v[48:63], v[202:205], v[214:217], v[48:63]
	ds_read_b128 v[136:139], v114 offset:26624
	ds_read_b128 v[140:143], v121 offset:40960
	v_mfma_f32_32x32x16_bf16 v[32:47], v[202:205], v[244:247], v[32:47]
	ds_read_b128 v[144:147], v121 offset:43008
	ds_read_b128 v[128:131], v109 offset:18432
	v_mfma_f32_32x32x16_bf16 v[150:165], v[202:205], v[250:253], v[150:165]
	v_mfma_f32_32x32x16_bf16 v[166:181], v[202:205], v[74:77], v[166:181]
	ds_read_b128 v[202:205], v115 offset:16384
	v_mfma_f32_32x32x16_bf16 v[16:31], v[206:209], v[214:217], v[16:31]
	ds_read_b128 v[214:217], v119 offset:24576
	v_mfma_f32_32x32x16_bf16 v[0:15], v[206:209], v[244:247], v[0:15]
	ds_read_b128 v[244:247], v119 offset:26624
	v_mfma_f32_32x32x16_bf16 v[184:199], v[206:209], v[250:253], v[184:199]
	ds_read_b128 v[250:253], v122 offset:40960
	v_mfma_f32_32x32x16_bf16 v[226:241], v[206:209], v[74:77], v[226:241]
	ds_read_b128 v[206:209], v115 offset:18432
	ds_read_b128 v[74:77], v122 offset:43008
	s_waitcnt lgkmcnt(6)
	v_mfma_f32_32x32x16_bf16 v[48:63], v[110:113], v[132:135], v[48:63]
	s_mov_b32 m0, s50
	v_lshl_add_u64 v[64:65], v[64:65], 0, s[44:45]
	global_load_lds_dwordx4 v[64:65], off sc1
	v_mfma_f32_32x32x16_bf16 v[32:47], v[110:113], v[136:139], v[32:47]
	global_load_lds_dwordx4 v[64:65], off offset:1024 sc1
	v_mfma_f32_32x32x16_bf16 v[150:165], v[110:113], v[140:143], v[150:165]
	s_mov_b32 m0, s53
	v_lshl_add_u64 v[66:67], v[66:67], 0, s[44:45]
	global_load_lds_dwordx4 v[66:67], off
	v_mfma_f32_32x32x16_bf16 v[166:181], v[110:113], v[144:147], v[166:181]
	global_load_lds_dwordx4 v[66:67], off offset:1024
	v_mfma_f32_32x32x16_bf16 v[16:31], v[128:131], v[132:135], v[16:31]
	s_mov_b32 m0, s56
	v_lshl_add_u64 v[148:149], v[66:67], 0, s[72:73]
	global_load_lds_dwordx4 v[148:149], off
	v_mfma_f32_32x32x16_bf16 v[0:15], v[128:131], v[136:139], v[0:15]
	global_load_lds_dwordx4 v[148:149], off offset:1024
	v_mfma_f32_32x32x16_bf16 v[184:199], v[128:131], v[140:143], v[184:199]
	v_mfma_f32_32x32x16_bf16 v[226:241], v[128:131], v[144:147], v[226:241]
	s_waitcnt vmcnt(6)
	s_waitcnt lgkmcnt(0)
	s_barrier
	ds_read_b128 v[110:113], v109 offset:32768
	ds_read_b128 v[132:135], v114 offset:40960
	v_mfma_f32_32x32x16_bf16 v[48:63], v[202:205], v[214:217], v[48:63]
	ds_read_b128 v[136:139], v114 offset:43008
	ds_read_b128 v[140:143], v121 offset:57344
	v_mfma_f32_32x32x16_bf16 v[32:47], v[202:205], v[244:247], v[32:47]
	ds_read_b128 v[144:147], v121 offset:59392
	ds_read_b128 v[128:131], v109 offset:34816
	v_mfma_f32_32x32x16_bf16 v[150:165], v[202:205], v[250:253], v[150:165]
	v_mfma_f32_32x32x16_bf16 v[166:181], v[202:205], v[74:77], v[166:181]
	ds_read_b128 v[202:205], v115 offset:32768
	v_mfma_f32_32x32x16_bf16 v[16:31], v[206:209], v[214:217], v[16:31]
	ds_read_b128 v[214:217], v119 offset:40960
	v_mfma_f32_32x32x16_bf16 v[0:15], v[206:209], v[244:247], v[0:15]
	ds_read_b128 v[244:247], v119 offset:43008
	v_mfma_f32_32x32x16_bf16 v[184:199], v[206:209], v[250:253], v[184:199]
	ds_read_b128 v[250:253], v122 offset:57344
	v_mfma_f32_32x32x16_bf16 v[226:241], v[206:209], v[74:77], v[226:241]
	ds_read_b128 v[206:209], v115 offset:34816
	ds_read_b128 v[74:77], v122 offset:59392
	s_waitcnt lgkmcnt(6)
	v_mfma_f32_32x32x16_bf16 v[48:63], v[110:113], v[132:135], v[48:63]
	s_mov_b32 m0, s51
	v_lshl_add_u64 v[64:65], v[64:65], 0, s[44:45]
	global_load_lds_dwordx4 v[64:65], off sc1
	v_mfma_f32_32x32x16_bf16 v[32:47], v[110:113], v[136:139], v[32:47]
	global_load_lds_dwordx4 v[64:65], off offset:1024 sc1
	v_mfma_f32_32x32x16_bf16 v[150:165], v[110:113], v[140:143], v[150:165]
	s_mov_b32 m0, s54
	v_lshl_add_u64 v[66:67], v[66:67], 0, s[44:45]
	global_load_lds_dwordx4 v[66:67], off
	v_mfma_f32_32x32x16_bf16 v[166:181], v[110:113], v[144:147], v[166:181]
	global_load_lds_dwordx4 v[66:67], off offset:1024
	v_mfma_f32_32x32x16_bf16 v[16:31], v[128:131], v[132:135], v[16:31]
	s_mov_b32 m0, s57
	v_lshl_add_u64 v[148:149], v[66:67], 0, s[72:73]
	global_load_lds_dwordx4 v[148:149], off
	v_mfma_f32_32x32x16_bf16 v[0:15], v[128:131], v[136:139], v[0:15]
	global_load_lds_dwordx4 v[148:149], off offset:1024
	v_mfma_f32_32x32x16_bf16 v[184:199], v[128:131], v[140:143], v[184:199]
	v_mfma_f32_32x32x16_bf16 v[226:241], v[128:131], v[144:147], v[226:241]
	s_waitcnt vmcnt(6)
	s_waitcnt lgkmcnt(0)
	s_barrier
	ds_read_b128 v[110:113], v109
	ds_read_b128 v[132:135], v114 offset:8192
	v_mfma_f32_32x32x16_bf16 v[48:63], v[202:205], v[214:217], v[48:63]
	ds_read_b128 v[136:139], v114 offset:10240
	ds_read_b128 v[140:143], v114 offset:49152
	v_mfma_f32_32x32x16_bf16 v[32:47], v[202:205], v[244:247], v[32:47]
	ds_read_b128 v[144:147], v114 offset:51200
	ds_read_b128 v[128:131], v109 offset:2048
	v_mfma_f32_32x32x16_bf16 v[150:165], v[202:205], v[250:253], v[150:165]
	v_mfma_f32_32x32x16_bf16 v[166:181], v[202:205], v[74:77], v[166:181]
	ds_read_b128 v[202:205], v115
	v_mfma_f32_32x32x16_bf16 v[16:31], v[206:209], v[214:217], v[16:31]
	ds_read_b128 v[214:217], v119 offset:8192
	v_mfma_f32_32x32x16_bf16 v[0:15], v[206:209], v[244:247], v[0:15]
	ds_read_b128 v[244:247], v119 offset:10240
	v_mfma_f32_32x32x16_bf16 v[184:199], v[206:209], v[250:253], v[184:199]
	ds_read_b128 v[250:253], v119 offset:49152
	v_mfma_f32_32x32x16_bf16 v[226:241], v[206:209], v[74:77], v[226:241]
	ds_read_b128 v[206:209], v115 offset:2048
	ds_read_b128 v[74:77], v119 offset:51200
	s_waitcnt lgkmcnt(6)
	v_mfma_f32_32x32x16_bf16 v[48:63], v[110:113], v[132:135], v[48:63]
	s_mov_b32 m0, s52
	v_lshl_add_u64 v[64:65], v[64:65], 0, s[44:45]
	global_load_lds_dwordx4 v[64:65], off sc1
	v_mfma_f32_32x32x16_bf16 v[32:47], v[110:113], v[136:139], v[32:47]
	global_load_lds_dwordx4 v[64:65], off offset:1024 sc1
	v_mfma_f32_32x32x16_bf16 v[150:165], v[110:113], v[140:143], v[150:165]
	s_mov_b32 m0, s55
	v_lshl_add_u64 v[66:67], v[66:67], 0, s[44:45]
	global_load_lds_dwordx4 v[66:67], off
	v_mfma_f32_32x32x16_bf16 v[166:181], v[110:113], v[144:147], v[166:181]
	global_load_lds_dwordx4 v[66:67], off offset:1024
	v_mfma_f32_32x32x16_bf16 v[16:31], v[128:131], v[132:135], v[16:31]
	s_mov_b32 m0, s58
	v_lshl_add_u64 v[148:149], v[66:67], 0, s[72:73]
	global_load_lds_dwordx4 v[148:149], off
	v_mfma_f32_32x32x16_bf16 v[0:15], v[128:131], v[136:139], v[0:15]
	global_load_lds_dwordx4 v[148:149], off offset:1024
	v_mfma_f32_32x32x16_bf16 v[184:199], v[128:131], v[140:143], v[184:199]
	v_mfma_f32_32x32x16_bf16 v[226:241], v[128:131], v[144:147], v[226:241]
	s_waitcnt vmcnt(6)
	s_waitcnt lgkmcnt(0)
	s_barrier
	ds_read_b128 v[110:113], v109 offset:16384
	ds_read_b128 v[132:135], v114 offset:24576
	v_mfma_f32_32x32x16_bf16 v[48:63], v[202:205], v[214:217], v[48:63]
	ds_read_b128 v[136:139], v114 offset:26624
	ds_read_b128 v[140:143], v121 offset:40960
	v_mfma_f32_32x32x16_bf16 v[32:47], v[202:205], v[244:247], v[32:47]
	ds_read_b128 v[144:147], v121 offset:43008
	ds_read_b128 v[128:131], v109 offset:18432
	v_mfma_f32_32x32x16_bf16 v[150:165], v[202:205], v[250:253], v[150:165]
	v_mfma_f32_32x32x16_bf16 v[166:181], v[202:205], v[74:77], v[166:181]
	ds_read_b128 v[202:205], v115 offset:16384
	v_mfma_f32_32x32x16_bf16 v[16:31], v[206:209], v[214:217], v[16:31]
	ds_read_b128 v[214:217], v119 offset:24576
	v_mfma_f32_32x32x16_bf16 v[0:15], v[206:209], v[244:247], v[0:15]
	ds_read_b128 v[244:247], v119 offset:26624
	v_mfma_f32_32x32x16_bf16 v[184:199], v[206:209], v[250:253], v[184:199]
	ds_read_b128 v[250:253], v122 offset:40960
	v_mfma_f32_32x32x16_bf16 v[226:241], v[206:209], v[74:77], v[226:241]
	ds_read_b128 v[206:209], v115 offset:18432
	ds_read_b128 v[74:77], v122 offset:43008
	s_waitcnt lgkmcnt(6)
	v_mfma_f32_32x32x16_bf16 v[48:63], v[110:113], v[132:135], v[48:63]
	s_mov_b32 m0, s50
	v_lshl_add_u64 v[64:65], v[64:65], 0, s[44:45]
	global_load_lds_dwordx4 v[64:65], off sc1
	v_mfma_f32_32x32x16_bf16 v[32:47], v[110:113], v[136:139], v[32:47]
	global_load_lds_dwordx4 v[64:65], off offset:1024 sc1
	v_mfma_f32_32x32x16_bf16 v[150:165], v[110:113], v[140:143], v[150:165]
	s_mov_b32 m0, s53
	v_lshl_add_u64 v[66:67], v[66:67], 0, s[44:45]
	global_load_lds_dwordx4 v[66:67], off
	v_mfma_f32_32x32x16_bf16 v[166:181], v[110:113], v[144:147], v[166:181]
	global_load_lds_dwordx4 v[66:67], off offset:1024
	v_mfma_f32_32x32x16_bf16 v[16:31], v[128:131], v[132:135], v[16:31]
	s_mov_b32 m0, s56
	v_lshl_add_u64 v[148:149], v[66:67], 0, s[72:73]
	global_load_lds_dwordx4 v[148:149], off
	v_mfma_f32_32x32x16_bf16 v[0:15], v[128:131], v[136:139], v[0:15]
	global_load_lds_dwordx4 v[148:149], off offset:1024
	v_mfma_f32_32x32x16_bf16 v[184:199], v[128:131], v[140:143], v[184:199]
	v_mfma_f32_32x32x16_bf16 v[226:241], v[128:131], v[144:147], v[226:241]
	s_waitcnt vmcnt(6)
	s_waitcnt lgkmcnt(0)
	s_barrier
	ds_read_b128 v[110:113], v109 offset:32768
	ds_read_b128 v[132:135], v114 offset:40960
	v_mfma_f32_32x32x16_bf16 v[48:63], v[202:205], v[214:217], v[48:63]
	ds_read_b128 v[136:139], v114 offset:43008
	ds_read_b128 v[140:143], v121 offset:57344
	v_mfma_f32_32x32x16_bf16 v[32:47], v[202:205], v[244:247], v[32:47]
	ds_read_b128 v[144:147], v121 offset:59392
	ds_read_b128 v[128:131], v109 offset:34816
	v_mfma_f32_32x32x16_bf16 v[150:165], v[202:205], v[250:253], v[150:165]
	v_mfma_f32_32x32x16_bf16 v[166:181], v[202:205], v[74:77], v[166:181]
	ds_read_b128 v[202:205], v115 offset:32768
	v_mfma_f32_32x32x16_bf16 v[16:31], v[206:209], v[214:217], v[16:31]
	ds_read_b128 v[214:217], v119 offset:40960
	v_mfma_f32_32x32x16_bf16 v[0:15], v[206:209], v[244:247], v[0:15]
	ds_read_b128 v[244:247], v119 offset:43008
	v_mfma_f32_32x32x16_bf16 v[184:199], v[206:209], v[250:253], v[184:199]
	ds_read_b128 v[250:253], v122 offset:57344
	v_mfma_f32_32x32x16_bf16 v[226:241], v[206:209], v[74:77], v[226:241]
	ds_read_b128 v[206:209], v115 offset:34816
	ds_read_b128 v[74:77], v122 offset:59392
	s_waitcnt lgkmcnt(6)
	v_mfma_f32_32x32x16_bf16 v[48:63], v[110:113], v[132:135], v[48:63]
	s_mov_b32 m0, s51
	v_lshl_add_u64 v[64:65], v[64:65], 0, s[44:45]
	global_load_lds_dwordx4 v[64:65], off sc1
	v_mfma_f32_32x32x16_bf16 v[32:47], v[110:113], v[136:139], v[32:47]
	global_load_lds_dwordx4 v[64:65], off offset:1024 sc1
	v_mfma_f32_32x32x16_bf16 v[150:165], v[110:113], v[140:143], v[150:165]
	s_mov_b32 m0, s54
	v_lshl_add_u64 v[66:67], v[66:67], 0, s[44:45]
	global_load_lds_dwordx4 v[66:67], off
	v_mfma_f32_32x32x16_bf16 v[166:181], v[110:113], v[144:147], v[166:181]
	global_load_lds_dwordx4 v[66:67], off offset:1024
	v_mfma_f32_32x32x16_bf16 v[16:31], v[128:131], v[132:135], v[16:31]
	s_mov_b32 m0, s57
	v_lshl_add_u64 v[148:149], v[66:67], 0, s[72:73]
	global_load_lds_dwordx4 v[148:149], off
	v_mfma_f32_32x32x16_bf16 v[0:15], v[128:131], v[136:139], v[0:15]
	global_load_lds_dwordx4 v[148:149], off offset:1024
	v_mfma_f32_32x32x16_bf16 v[184:199], v[128:131], v[140:143], v[184:199]
	v_mfma_f32_32x32x16_bf16 v[226:241], v[128:131], v[144:147], v[226:241]
	s_waitcnt vmcnt(6)
	s_waitcnt lgkmcnt(0)
	s_barrier
	ds_read_b128 v[110:113], v109
	ds_read_b128 v[132:135], v114 offset:8192
	v_mfma_f32_32x32x16_bf16 v[48:63], v[202:205], v[214:217], v[48:63]
	ds_read_b128 v[136:139], v114 offset:10240
	ds_read_b128 v[140:143], v114 offset:49152
	v_mfma_f32_32x32x16_bf16 v[32:47], v[202:205], v[244:247], v[32:47]
	ds_read_b128 v[144:147], v114 offset:51200
	ds_read_b128 v[128:131], v109 offset:2048
	v_mfma_f32_32x32x16_bf16 v[150:165], v[202:205], v[250:253], v[150:165]
	v_mfma_f32_32x32x16_bf16 v[166:181], v[202:205], v[74:77], v[166:181]
	ds_read_b128 v[202:205], v115
	v_mfma_f32_32x32x16_bf16 v[16:31], v[206:209], v[214:217], v[16:31]
	ds_read_b128 v[214:217], v119 offset:8192
	v_mfma_f32_32x32x16_bf16 v[0:15], v[206:209], v[244:247], v[0:15]
	ds_read_b128 v[244:247], v119 offset:10240
	v_mfma_f32_32x32x16_bf16 v[184:199], v[206:209], v[250:253], v[184:199]
	ds_read_b128 v[250:253], v119 offset:49152
	v_mfma_f32_32x32x16_bf16 v[226:241], v[206:209], v[74:77], v[226:241]
	ds_read_b128 v[206:209], v115 offset:2048
	ds_read_b128 v[74:77], v119 offset:51200
	s_waitcnt lgkmcnt(6)
	v_mfma_f32_32x32x16_bf16 v[48:63], v[110:113], v[132:135], v[48:63]
	s_mov_b32 m0, s52
	v_lshl_add_u64 v[64:65], v[64:65], 0, s[44:45]
	global_load_lds_dwordx4 v[64:65], off sc1
	v_mfma_f32_32x32x16_bf16 v[32:47], v[110:113], v[136:139], v[32:47]
	global_load_lds_dwordx4 v[64:65], off offset:1024 sc1
	v_mfma_f32_32x32x16_bf16 v[150:165], v[110:113], v[140:143], v[150:165]
	s_mov_b32 m0, s55
	v_lshl_add_u64 v[66:67], v[66:67], 0, s[44:45]
	global_load_lds_dwordx4 v[66:67], off
	v_mfma_f32_32x32x16_bf16 v[166:181], v[110:113], v[144:147], v[166:181]
	global_load_lds_dwordx4 v[66:67], off offset:1024
	v_mfma_f32_32x32x16_bf16 v[16:31], v[128:131], v[132:135], v[16:31]
	s_mov_b32 m0, s58
	v_lshl_add_u64 v[148:149], v[66:67], 0, s[72:73]
	global_load_lds_dwordx4 v[148:149], off
	v_mfma_f32_32x32x16_bf16 v[0:15], v[128:131], v[136:139], v[0:15]
	global_load_lds_dwordx4 v[148:149], off offset:1024
	v_mfma_f32_32x32x16_bf16 v[184:199], v[128:131], v[140:143], v[184:199]
	v_mfma_f32_32x32x16_bf16 v[226:241], v[128:131], v[144:147], v[226:241]
	s_waitcnt vmcnt(6)
	s_waitcnt lgkmcnt(0)
	s_barrier
	ds_read_b128 v[110:113], v109 offset:16384
	ds_read_b128 v[132:135], v114 offset:24576
	v_mfma_f32_32x32x16_bf16 v[48:63], v[202:205], v[214:217], v[48:63]
	ds_read_b128 v[136:139], v114 offset:26624
	ds_read_b128 v[140:143], v121 offset:40960
	v_mfma_f32_32x32x16_bf16 v[32:47], v[202:205], v[244:247], v[32:47]
	ds_read_b128 v[144:147], v121 offset:43008
	ds_read_b128 v[128:131], v109 offset:18432
	v_mfma_f32_32x32x16_bf16 v[150:165], v[202:205], v[250:253], v[150:165]
	v_mfma_f32_32x32x16_bf16 v[166:181], v[202:205], v[74:77], v[166:181]
	ds_read_b128 v[202:205], v115 offset:16384
	v_mfma_f32_32x32x16_bf16 v[16:31], v[206:209], v[214:217], v[16:31]
	ds_read_b128 v[214:217], v119 offset:24576
	v_mfma_f32_32x32x16_bf16 v[0:15], v[206:209], v[244:247], v[0:15]
	ds_read_b128 v[244:247], v119 offset:26624
	v_mfma_f32_32x32x16_bf16 v[184:199], v[206:209], v[250:253], v[184:199]
	ds_read_b128 v[250:253], v122 offset:40960
	v_mfma_f32_32x32x16_bf16 v[226:241], v[206:209], v[74:77], v[226:241]
	ds_read_b128 v[206:209], v115 offset:18432
	ds_read_b128 v[74:77], v122 offset:43008
	s_waitcnt lgkmcnt(6)
	v_mfma_f32_32x32x16_bf16 v[48:63], v[110:113], v[132:135], v[48:63]
	s_mov_b32 m0, s50
	v_lshl_add_u64 v[64:65], v[64:65], 0, s[44:45]
	global_load_lds_dwordx4 v[64:65], off sc1
	v_mfma_f32_32x32x16_bf16 v[32:47], v[110:113], v[136:139], v[32:47]
	global_load_lds_dwordx4 v[64:65], off offset:1024 sc1
	v_mfma_f32_32x32x16_bf16 v[150:165], v[110:113], v[140:143], v[150:165]
	s_mov_b32 m0, s53
	v_lshl_add_u64 v[66:67], v[66:67], 0, s[44:45]
	global_load_lds_dwordx4 v[66:67], off
	v_mfma_f32_32x32x16_bf16 v[166:181], v[110:113], v[144:147], v[166:181]
	global_load_lds_dwordx4 v[66:67], off offset:1024
	v_mfma_f32_32x32x16_bf16 v[16:31], v[128:131], v[132:135], v[16:31]
	s_mov_b32 m0, s56
	v_lshl_add_u64 v[148:149], v[66:67], 0, s[72:73]
	global_load_lds_dwordx4 v[148:149], off
	v_mfma_f32_32x32x16_bf16 v[0:15], v[128:131], v[136:139], v[0:15]
	global_load_lds_dwordx4 v[148:149], off offset:1024
	v_mfma_f32_32x32x16_bf16 v[184:199], v[128:131], v[140:143], v[184:199]
	v_mfma_f32_32x32x16_bf16 v[226:241], v[128:131], v[144:147], v[226:241]
	s_waitcnt vmcnt(6)
	s_waitcnt lgkmcnt(0)
	s_barrier
	ds_read_b128 v[110:113], v109 offset:32768
	ds_read_b128 v[132:135], v114 offset:40960
	v_mfma_f32_32x32x16_bf16 v[48:63], v[202:205], v[214:217], v[48:63]
	ds_read_b128 v[136:139], v114 offset:43008
	ds_read_b128 v[140:143], v121 offset:57344
	v_mfma_f32_32x32x16_bf16 v[32:47], v[202:205], v[244:247], v[32:47]
	ds_read_b128 v[144:147], v121 offset:59392
	ds_read_b128 v[128:131], v109 offset:34816
	v_mfma_f32_32x32x16_bf16 v[150:165], v[202:205], v[250:253], v[150:165]
	v_mfma_f32_32x32x16_bf16 v[166:181], v[202:205], v[74:77], v[166:181]
	ds_read_b128 v[202:205], v115 offset:32768
	v_mfma_f32_32x32x16_bf16 v[16:31], v[206:209], v[214:217], v[16:31]
	ds_read_b128 v[214:217], v119 offset:40960
	v_mfma_f32_32x32x16_bf16 v[0:15], v[206:209], v[244:247], v[0:15]
	ds_read_b128 v[244:247], v119 offset:43008
	v_mfma_f32_32x32x16_bf16 v[184:199], v[206:209], v[250:253], v[184:199]
	ds_read_b128 v[250:253], v122 offset:57344
	v_mfma_f32_32x32x16_bf16 v[226:241], v[206:209], v[74:77], v[226:241]
	ds_read_b128 v[206:209], v115 offset:34816
	ds_read_b128 v[74:77], v122 offset:59392
	s_waitcnt lgkmcnt(6)
	v_mfma_f32_32x32x16_bf16 v[48:63], v[110:113], v[132:135], v[48:63]
	s_mov_b32 m0, s51
	v_lshl_add_u64 v[64:65], v[64:65], 0, s[44:45]
	global_load_lds_dwordx4 v[64:65], off sc1
	v_mfma_f32_32x32x16_bf16 v[32:47], v[110:113], v[136:139], v[32:47]
	global_load_lds_dwordx4 v[64:65], off offset:1024 sc1
	v_mfma_f32_32x32x16_bf16 v[150:165], v[110:113], v[140:143], v[150:165]
	s_mov_b32 m0, s54
	v_lshl_add_u64 v[66:67], v[66:67], 0, s[44:45]
	global_load_lds_dwordx4 v[66:67], off
	v_mfma_f32_32x32x16_bf16 v[166:181], v[110:113], v[144:147], v[166:181]
	global_load_lds_dwordx4 v[66:67], off offset:1024
	v_mfma_f32_32x32x16_bf16 v[16:31], v[128:131], v[132:135], v[16:31]
	s_mov_b32 m0, s57
	v_lshl_add_u64 v[148:149], v[66:67], 0, s[72:73]
	global_load_lds_dwordx4 v[148:149], off
	v_mfma_f32_32x32x16_bf16 v[0:15], v[128:131], v[136:139], v[0:15]
	global_load_lds_dwordx4 v[148:149], off offset:1024
	v_mfma_f32_32x32x16_bf16 v[184:199], v[128:131], v[140:143], v[184:199]
	v_mfma_f32_32x32x16_bf16 v[226:241], v[128:131], v[144:147], v[226:241]
	s_waitcnt vmcnt(6)
	s_waitcnt lgkmcnt(0)
	s_barrier
	ds_read_b128 v[110:113], v109
	ds_read_b128 v[132:135], v114 offset:8192
	v_mfma_f32_32x32x16_bf16 v[48:63], v[202:205], v[214:217], v[48:63]
	ds_read_b128 v[136:139], v114 offset:10240
	ds_read_b128 v[140:143], v114 offset:49152
	v_mfma_f32_32x32x16_bf16 v[32:47], v[202:205], v[244:247], v[32:47]
	ds_read_b128 v[144:147], v114 offset:51200
	ds_read_b128 v[128:131], v109 offset:2048
	v_mfma_f32_32x32x16_bf16 v[150:165], v[202:205], v[250:253], v[150:165]
	v_mfma_f32_32x32x16_bf16 v[166:181], v[202:205], v[74:77], v[166:181]
	ds_read_b128 v[202:205], v115
	v_mfma_f32_32x32x16_bf16 v[16:31], v[206:209], v[214:217], v[16:31]
	ds_read_b128 v[214:217], v119 offset:8192
	v_mfma_f32_32x32x16_bf16 v[0:15], v[206:209], v[244:247], v[0:15]
	ds_read_b128 v[244:247], v119 offset:10240
	v_mfma_f32_32x32x16_bf16 v[184:199], v[206:209], v[250:253], v[184:199]
	ds_read_b128 v[250:253], v119 offset:49152
	v_mfma_f32_32x32x16_bf16 v[226:241], v[206:209], v[74:77], v[226:241]
	ds_read_b128 v[206:209], v115 offset:2048
	ds_read_b128 v[74:77], v119 offset:51200
	s_waitcnt lgkmcnt(6)
	v_mfma_f32_32x32x16_bf16 v[48:63], v[110:113], v[132:135], v[48:63]
	s_mov_b32 m0, s52
	v_lshl_add_u64 v[64:65], v[64:65], 0, s[44:45]
	global_load_lds_dwordx4 v[64:65], off sc1
	v_mfma_f32_32x32x16_bf16 v[32:47], v[110:113], v[136:139], v[32:47]
	global_load_lds_dwordx4 v[64:65], off offset:1024 sc1
	v_mfma_f32_32x32x16_bf16 v[150:165], v[110:113], v[140:143], v[150:165]
	s_mov_b32 m0, s55
	v_lshl_add_u64 v[66:67], v[66:67], 0, s[44:45]
	global_load_lds_dwordx4 v[66:67], off
	v_mfma_f32_32x32x16_bf16 v[166:181], v[110:113], v[144:147], v[166:181]
	global_load_lds_dwordx4 v[66:67], off offset:1024
	v_mfma_f32_32x32x16_bf16 v[16:31], v[128:131], v[132:135], v[16:31]
	s_mov_b32 m0, s58
	v_lshl_add_u64 v[148:149], v[66:67], 0, s[72:73]
	global_load_lds_dwordx4 v[148:149], off
	v_mfma_f32_32x32x16_bf16 v[0:15], v[128:131], v[136:139], v[0:15]
	global_load_lds_dwordx4 v[148:149], off offset:1024
	v_mfma_f32_32x32x16_bf16 v[184:199], v[128:131], v[140:143], v[184:199]
	v_mfma_f32_32x32x16_bf16 v[226:241], v[128:131], v[144:147], v[226:241]
	s_waitcnt vmcnt(6)
	s_waitcnt lgkmcnt(0)
	s_barrier
	ds_read_b128 v[110:113], v109 offset:16384
	ds_read_b128 v[132:135], v114 offset:24576
	v_mfma_f32_32x32x16_bf16 v[48:63], v[202:205], v[214:217], v[48:63]
	ds_read_b128 v[136:139], v114 offset:26624
	ds_read_b128 v[140:143], v121 offset:40960
	v_mfma_f32_32x32x16_bf16 v[32:47], v[202:205], v[244:247], v[32:47]
	ds_read_b128 v[144:147], v121 offset:43008
	ds_read_b128 v[128:131], v109 offset:18432
	v_mfma_f32_32x32x16_bf16 v[150:165], v[202:205], v[250:253], v[150:165]
	v_mfma_f32_32x32x16_bf16 v[166:181], v[202:205], v[74:77], v[166:181]
	ds_read_b128 v[202:205], v115 offset:16384
	v_mfma_f32_32x32x16_bf16 v[16:31], v[206:209], v[214:217], v[16:31]
	ds_read_b128 v[214:217], v119 offset:24576
	v_mfma_f32_32x32x16_bf16 v[0:15], v[206:209], v[244:247], v[0:15]
	ds_read_b128 v[244:247], v119 offset:26624
	v_mfma_f32_32x32x16_bf16 v[184:199], v[206:209], v[250:253], v[184:199]
	ds_read_b128 v[250:253], v122 offset:40960
	v_mfma_f32_32x32x16_bf16 v[226:241], v[206:209], v[74:77], v[226:241]
	ds_read_b128 v[206:209], v115 offset:18432
	ds_read_b128 v[74:77], v122 offset:43008
	s_waitcnt lgkmcnt(6)
	v_mfma_f32_32x32x16_bf16 v[48:63], v[110:113], v[132:135], v[48:63]
	s_mov_b32 m0, s50
	v_lshl_add_u64 v[64:65], v[64:65], 0, s[44:45]
	global_load_lds_dwordx4 v[64:65], off sc1
	v_mfma_f32_32x32x16_bf16 v[32:47], v[110:113], v[136:139], v[32:47]
	global_load_lds_dwordx4 v[64:65], off offset:1024 sc1
	v_mfma_f32_32x32x16_bf16 v[150:165], v[110:113], v[140:143], v[150:165]
	s_mov_b32 m0, s53
	v_lshl_add_u64 v[66:67], v[66:67], 0, s[44:45]
	global_load_lds_dwordx4 v[66:67], off
	v_mfma_f32_32x32x16_bf16 v[166:181], v[110:113], v[144:147], v[166:181]
	global_load_lds_dwordx4 v[66:67], off offset:1024
	v_mfma_f32_32x32x16_bf16 v[16:31], v[128:131], v[132:135], v[16:31]
	s_mov_b32 m0, s56
	v_lshl_add_u64 v[148:149], v[66:67], 0, s[72:73]
	global_load_lds_dwordx4 v[148:149], off
	v_mfma_f32_32x32x16_bf16 v[0:15], v[128:131], v[136:139], v[0:15]
	global_load_lds_dwordx4 v[148:149], off offset:1024
	v_mfma_f32_32x32x16_bf16 v[184:199], v[128:131], v[140:143], v[184:199]
	v_mfma_f32_32x32x16_bf16 v[226:241], v[128:131], v[144:147], v[226:241]
	s_waitcnt vmcnt(6)
	s_waitcnt lgkmcnt(0)
	s_barrier
	ds_read_b128 v[110:113], v109 offset:32768
	ds_read_b128 v[132:135], v114 offset:40960
	v_mfma_f32_32x32x16_bf16 v[48:63], v[202:205], v[214:217], v[48:63]
	ds_read_b128 v[136:139], v114 offset:43008
	ds_read_b128 v[140:143], v121 offset:57344
	v_mfma_f32_32x32x16_bf16 v[32:47], v[202:205], v[244:247], v[32:47]
	ds_read_b128 v[144:147], v121 offset:59392
	ds_read_b128 v[128:131], v109 offset:34816
	v_mfma_f32_32x32x16_bf16 v[150:165], v[202:205], v[250:253], v[150:165]
	v_mfma_f32_32x32x16_bf16 v[166:181], v[202:205], v[74:77], v[166:181]
	ds_read_b128 v[202:205], v115 offset:32768
	v_mfma_f32_32x32x16_bf16 v[16:31], v[206:209], v[214:217], v[16:31]
	ds_read_b128 v[214:217], v119 offset:40960
	v_mfma_f32_32x32x16_bf16 v[0:15], v[206:209], v[244:247], v[0:15]
	ds_read_b128 v[244:247], v119 offset:43008
	v_mfma_f32_32x32x16_bf16 v[184:199], v[206:209], v[250:253], v[184:199]
	ds_read_b128 v[250:253], v122 offset:57344
	v_mfma_f32_32x32x16_bf16 v[226:241], v[206:209], v[74:77], v[226:241]
	ds_read_b128 v[206:209], v115 offset:34816
	ds_read_b128 v[74:77], v122 offset:59392
	s_waitcnt lgkmcnt(6)
	v_mfma_f32_32x32x16_bf16 v[48:63], v[110:113], v[132:135], v[48:63]
	s_mov_b32 m0, s51
	v_lshl_add_u64 v[64:65], v[64:65], 0, s[44:45]
	global_load_lds_dwordx4 v[64:65], off sc1
	v_mfma_f32_32x32x16_bf16 v[32:47], v[110:113], v[136:139], v[32:47]
	global_load_lds_dwordx4 v[64:65], off offset:1024 sc1
	v_mfma_f32_32x32x16_bf16 v[150:165], v[110:113], v[140:143], v[150:165]
	s_mov_b32 m0, s54
	v_lshl_add_u64 v[66:67], v[66:67], 0, s[44:45]
	global_load_lds_dwordx4 v[66:67], off
	v_mfma_f32_32x32x16_bf16 v[166:181], v[110:113], v[144:147], v[166:181]
	global_load_lds_dwordx4 v[66:67], off offset:1024
	v_mfma_f32_32x32x16_bf16 v[16:31], v[128:131], v[132:135], v[16:31]
	s_mov_b32 m0, s57
	v_lshl_add_u64 v[148:149], v[66:67], 0, s[72:73]
	global_load_lds_dwordx4 v[148:149], off
	v_mfma_f32_32x32x16_bf16 v[0:15], v[128:131], v[136:139], v[0:15]
	global_load_lds_dwordx4 v[148:149], off offset:1024
	v_mfma_f32_32x32x16_bf16 v[184:199], v[128:131], v[140:143], v[184:199]
	v_mfma_f32_32x32x16_bf16 v[226:241], v[128:131], v[144:147], v[226:241]
	s_waitcnt vmcnt(6)
	s_waitcnt lgkmcnt(0)
	s_barrier
	ds_read_b128 v[110:113], v109
	ds_read_b128 v[132:135], v114 offset:8192
	v_mfma_f32_32x32x16_bf16 v[48:63], v[202:205], v[214:217], v[48:63]
	ds_read_b128 v[136:139], v114 offset:10240
	ds_read_b128 v[140:143], v114 offset:49152
	v_mfma_f32_32x32x16_bf16 v[32:47], v[202:205], v[244:247], v[32:47]
	ds_read_b128 v[144:147], v114 offset:51200
	ds_read_b128 v[128:131], v109 offset:2048
	v_mfma_f32_32x32x16_bf16 v[150:165], v[202:205], v[250:253], v[150:165]
	v_mfma_f32_32x32x16_bf16 v[166:181], v[202:205], v[74:77], v[166:181]
	ds_read_b128 v[202:205], v115
	v_mfma_f32_32x32x16_bf16 v[16:31], v[206:209], v[214:217], v[16:31]
	ds_read_b128 v[214:217], v119 offset:8192
	v_mfma_f32_32x32x16_bf16 v[0:15], v[206:209], v[244:247], v[0:15]
	ds_read_b128 v[244:247], v119 offset:10240
	v_mfma_f32_32x32x16_bf16 v[184:199], v[206:209], v[250:253], v[184:199]
	ds_read_b128 v[250:253], v119 offset:49152
	v_mfma_f32_32x32x16_bf16 v[226:241], v[206:209], v[74:77], v[226:241]
	ds_read_b128 v[206:209], v115 offset:2048
	ds_read_b128 v[74:77], v119 offset:51200
	s_waitcnt lgkmcnt(6)
	v_mfma_f32_32x32x16_bf16 v[48:63], v[110:113], v[132:135], v[48:63]
	v_mfma_f32_32x32x16_bf16 v[32:47], v[110:113], v[136:139], v[32:47]
	v_mfma_f32_32x32x16_bf16 v[150:165], v[110:113], v[140:143], v[150:165]
	v_mfma_f32_32x32x16_bf16 v[166:181], v[110:113], v[144:147], v[166:181]
	v_mfma_f32_32x32x16_bf16 v[16:31], v[128:131], v[132:135], v[16:31]
	v_mfma_f32_32x32x16_bf16 v[0:15], v[128:131], v[136:139], v[0:15]
	v_mfma_f32_32x32x16_bf16 v[184:199], v[128:131], v[140:143], v[184:199]
	v_mfma_f32_32x32x16_bf16 v[226:241], v[128:131], v[144:147], v[226:241]
	s_waitcnt vmcnt(0)
	s_waitcnt lgkmcnt(0)
	s_barrier
	ds_read_b128 v[110:113], v109 offset:16384
	ds_read_b128 v[132:135], v114 offset:24576
	v_mfma_f32_32x32x16_bf16 v[48:63], v[202:205], v[214:217], v[48:63]
	ds_read_b128 v[136:139], v114 offset:26624
	ds_read_b128 v[140:143], v121 offset:40960
	v_mfma_f32_32x32x16_bf16 v[32:47], v[202:205], v[244:247], v[32:47]
	ds_read_b128 v[144:147], v121 offset:43008
	ds_read_b128 v[128:131], v109 offset:18432
	v_mfma_f32_32x32x16_bf16 v[150:165], v[202:205], v[250:253], v[150:165]
	v_mfma_f32_32x32x16_bf16 v[166:181], v[202:205], v[74:77], v[166:181]
	ds_read_b128 v[202:205], v115 offset:16384
	v_mfma_f32_32x32x16_bf16 v[16:31], v[206:209], v[214:217], v[16:31]
	ds_read_b128 v[214:217], v119 offset:24576
	v_mfma_f32_32x32x16_bf16 v[0:15], v[206:209], v[244:247], v[0:15]
	ds_read_b128 v[244:247], v119 offset:26624
	v_mfma_f32_32x32x16_bf16 v[184:199], v[206:209], v[250:253], v[184:199]
	ds_read_b128 v[250:253], v122 offset:40960
	v_mfma_f32_32x32x16_bf16 v[226:241], v[206:209], v[74:77], v[226:241]
	ds_read_b128 v[206:209], v115 offset:18432
	ds_read_b128 v[74:77], v122 offset:43008
	s_waitcnt lgkmcnt(6)
	v_mfma_f32_32x32x16_bf16 v[48:63], v[110:113], v[132:135], v[48:63]
	v_mfma_f32_32x32x16_bf16 v[32:47], v[110:113], v[136:139], v[32:47]
	v_mfma_f32_32x32x16_bf16 v[150:165], v[110:113], v[140:143], v[150:165]
	v_mfma_f32_32x32x16_bf16 v[166:181], v[110:113], v[144:147], v[166:181]
	v_mfma_f32_32x32x16_bf16 v[16:31], v[128:131], v[132:135], v[16:31]
	v_mfma_f32_32x32x16_bf16 v[0:15], v[128:131], v[136:139], v[0:15]
	v_mfma_f32_32x32x16_bf16 v[184:199], v[128:131], v[140:143], v[184:199]
	v_mfma_f32_32x32x16_bf16 v[226:241], v[128:131], v[144:147], v[226:241]
	s_waitcnt lgkmcnt(0)
	v_mfma_f32_32x32x16_bf16 v[48:63], v[202:205], v[214:217], v[48:63]
	v_mfma_f32_32x32x16_bf16 v[32:47], v[202:205], v[244:247], v[32:47]
	v_mfma_f32_32x32x16_bf16 v[150:165], v[202:205], v[250:253], v[150:165]
	v_mfma_f32_32x32x16_bf16 v[166:181], v[202:205], v[74:77], v[166:181]
	v_mfma_f32_32x32x16_bf16 v[16:31], v[206:209], v[214:217], v[16:31]
	v_mfma_f32_32x32x16_bf16 v[0:15], v[206:209], v[244:247], v[0:15]
	v_mfma_f32_32x32x16_bf16 v[184:199], v[206:209], v[250:253], v[184:199]
	v_mfma_f32_32x32x16_bf16 v[226:241], v[206:209], v[74:77], v[226:241]
	v_add_u32_e32 v77, 0x4400, v88
	v_add_u32_e32 v76, 0x6000, v88
	v_add_u32_e32 v75, 0x6400, v88
	v_add_u32_e32 v74, 0x8000, v88
	s_branch .Lgu_post
.Lgu_single:
	v_add_u32_e32 v109, v89, v91
	v_add_u32_e32 v110, v90, v91
	v_add_u32_e32 v111, v89, v92
	v_add_u32_e32 v112, v90, v92
	v_readfirstlane_b32 s52, v88
	s_mov_b64 s[50:51], 0x4000
	s_add_u32 s53, s52, 0x4000
	s_add_u32 s54, s52, 0x8000
	s_add_u32 s55, s52, 0xc000
	s_add_u32 s56, s52, 0x2000
	s_add_u32 s57, s52, 0x6000
	s_add_u32 s58, s52, 0xa000
	s_add_u32 s59, s52, 0xe000
	v_lshl_add_u64 v[64:65], v[64:65], 0, s[50:51]
	v_lshl_add_u64 v[66:67], v[66:67], 0, s[50:51]
	s_waitcnt lgkmcnt(0)
	s_barrier
	ds_read_b128 v[128:131], v109
	ds_read_b128 v[136:139], v110 offset:8192
	ds_read_b128 v[140:143], v110 offset:10240
	ds_read_b128 v[132:135], v109 offset:2048
	ds_read_b128 v[144:147], v111
	ds_read_b128 v[152:155], v112 offset:8192
	ds_read_b128 v[156:159], v112 offset:10240
	ds_read_b128 v[148:151], v111 offset:2048
	s_mov_b32 m0, s55
	v_lshl_add_u64 v[64:65], v[64:65], 0, s[44:45]
	global_load_lds_dwordx4 v[64:65], off sc1
	global_load_lds_dwordx4 v[64:65], off offset:1024 sc1
	s_mov_b32 m0, s59
	v_lshl_add_u64 v[66:67], v[66:67], 0, s[44:45]
	global_load_lds_dwordx4 v[66:67], off
	global_load_lds_dwordx4 v[66:67], off offset:1024
	s_waitcnt vmcnt(8)
	s_waitcnt lgkmcnt(0)
	s_barrier
	ds_read_b128 v[160:163], v109 offset:16384
	ds_read_b128 v[168:171], v110 offset:24576
	v_mfma_f32_32x32x16_bf16 v[48:63], v[128:131], v[136:139], 0
	ds_read_b128 v[172:175], v110 offset:26624
	ds_read_b128 v[164:167], v109 offset:18432
	v_mfma_f32_32x32x16_bf16 v[32:47], v[128:131], v[140:143], 0
	ds_read_b128 v[176:179], v111 offset:16384
	ds_read_b128 v[188:191], v112 offset:24576
	v_mfma_f32_32x32x16_bf16 v[16:31], v[132:135], v[136:139], 0
	ds_read_b128 v[192:195], v112 offset:26624
	ds_read_b128 v[184:187], v111 offset:18432
	v_mfma_f32_32x32x16_bf16 v[0:15], v[132:135], v[140:143], 0
	s_mov_b32 m0, s52
	v_lshl_add_u64 v[64:65], v[64:65], 0, s[44:45]
	global_load_lds_dwordx4 v[64:65], off sc1
	v_mfma_f32_32x32x16_bf16 v[48:63], v[144:147], v[152:155], v[48:63]
	global_load_lds_dwordx4 v[64:65], off offset:1024 sc1
	v_mfma_f32_32x32x16_bf16 v[32:47], v[144:147], v[156:159], v[32:47]
	s_mov_b32 m0, s56
	v_lshl_add_u64 v[66:67], v[66:67], 0, s[44:45]
	global_load_lds_dwordx4 v[66:67], off
	v_mfma_f32_32x32x16_bf16 v[16:31], v[148:151], v[152:155], v[16:31]
	global_load_lds_dwordx4 v[66:67], off offset:1024
	v_mfma_f32_32x32x16_bf16 v[0:15], v[148:151], v[156:159], v[0:15]
	s_waitcnt vmcnt(8)
	s_waitcnt lgkmcnt(0)
	s_barrier
	ds_read_b128 v[128:131], v109 offset:32768
	ds_read_b128 v[136:139], v110 offset:40960
	v_mfma_f32_32x32x16_bf16 v[48:63], v[160:163], v[168:171], v[48:63]
	ds_read_b128 v[140:143], v110 offset:43008
	ds_read_b128 v[132:135], v109 offset:34816
	v_mfma_f32_32x32x16_bf16 v[32:47], v[160:163], v[172:175], v[32:47]
	ds_read_b128 v[144:147], v111 offset:32768
	ds_read_b128 v[152:155], v112 offset:40960
	v_mfma_f32_32x32x16_bf16 v[16:31], v[164:167], v[168:171], v[16:31]
	ds_read_b128 v[156:159], v112 offset:43008
	ds_read_b128 v[148:151], v111 offset:34816
	v_mfma_f32_32x32x16_bf16 v[0:15], v[164:167], v[172:175], v[0:15]
	s_mov_b32 m0, s53
	v_lshl_add_u64 v[64:65], v[64:65], 0, s[44:45]
	global_load_lds_dwordx4 v[64:65], off sc1
	v_mfma_f32_32x32x16_bf16 v[48:63], v[176:179], v[188:191], v[48:63]
	global_load_lds_dwordx4 v[64:65], off offset:1024 sc1
	v_mfma_f32_32x32x16_bf16 v[32:47], v[176:179], v[192:195], v[32:47]
	s_mov_b32 m0, s57
	v_lshl_add_u64 v[66:67], v[66:67], 0, s[44:45]
	global_load_lds_dwordx4 v[66:67], off
	v_mfma_f32_32x32x16_bf16 v[16:31], v[184:187], v[188:191], v[16:31]
	global_load_lds_dwordx4 v[66:67], off offset:1024
	v_mfma_f32_32x32x16_bf16 v[0:15], v[184:187], v[192:195], v[0:15]
	s_waitcnt vmcnt(8)
	s_waitcnt lgkmcnt(0)
	s_barrier
	ds_read_b128 v[160:163], v109 offset:49152
	ds_read_b128 v[168:171], v110 offset:57344
	v_mfma_f32_32x32x16_bf16 v[48:63], v[128:131], v[136:139], v[48:63]
	ds_read_b128 v[172:175], v110 offset:59392
	ds_read_b128 v[164:167], v109 offset:51200
	v_mfma_f32_32x32x16_bf16 v[32:47], v[128:131], v[140:143], v[32:47]
	ds_read_b128 v[176:179], v111 offset:49152
	ds_read_b128 v[188:191], v112 offset:57344
	v_mfma_f32_32x32x16_bf16 v[16:31], v[132:135], v[136:139], v[16:31]
	ds_read_b128 v[192:195], v112 offset:59392
	ds_read_b128 v[184:187], v111 offset:51200
	v_mfma_f32_32x32x16_bf16 v[0:15], v[132:135], v[140:143], v[0:15]
	s_mov_b32 m0, s54
	v_lshl_add_u64 v[64:65], v[64:65], 0, s[44:45]
	global_load_lds_dwordx4 v[64:65], off sc1
	v_mfma_f32_32x32x16_bf16 v[48:63], v[144:147], v[152:155], v[48:63]
	global_load_lds_dwordx4 v[64:65], off offset:1024 sc1
	v_mfma_f32_32x32x16_bf16 v[32:47], v[144:147], v[156:159], v[32:47]
	s_mov_b32 m0, s58
	v_lshl_add_u64 v[66:67], v[66:67], 0, s[44:45]
	global_load_lds_dwordx4 v[66:67], off
	v_mfma_f32_32x32x16_bf16 v[16:31], v[148:151], v[152:155], v[16:31]
	global_load_lds_dwordx4 v[66:67], off offset:1024
	v_mfma_f32_32x32x16_bf16 v[0:15], v[148:151], v[156:159], v[0:15]
	s_waitcnt vmcnt(8)
	s_waitcnt lgkmcnt(0)
	s_barrier
	ds_read_b128 v[128:131], v109
	ds_read_b128 v[136:139], v110 offset:8192
	v_mfma_f32_32x32x16_bf16 v[48:63], v[160:163], v[168:171], v[48:63]
	ds_read_b128 v[140:143], v110 offset:10240
	ds_read_b128 v[132:135], v109 offset:2048
	v_mfma_f32_32x32x16_bf16 v[32:47], v[160:163], v[172:175], v[32:47]
	ds_read_b128 v[144:147], v111
	ds_read_b128 v[152:155], v112 offset:8192
	v_mfma_f32_32x32x16_bf16 v[16:31], v[164:167], v[168:171], v[16:31]
	ds_read_b128 v[156:159], v112 offset:10240
	ds_read_b128 v[148:151], v111 offset:2048
	v_mfma_f32_32x32x16_bf16 v[0:15], v[164:167], v[172:175], v[0:15]
	s_mov_b32 m0, s55
	v_lshl_add_u64 v[64:65], v[64:65], 0, s[44:45]
	global_load_lds_dwordx4 v[64:65], off sc1
	v_mfma_f32_32x32x16_bf16 v[48:63], v[176:179], v[188:191], v[48:63]
	global_load_lds_dwordx4 v[64:65], off offset:1024 sc1
	v_mfma_f32_32x32x16_bf16 v[32:47], v[176:179], v[192:195], v[32:47]
	s_mov_b32 m0, s59
	v_lshl_add_u64 v[66:67], v[66:67], 0, s[44:45]
	global_load_lds_dwordx4 v[66:67], off
	v_mfma_f32_32x32x16_bf16 v[16:31], v[184:187], v[188:191], v[16:31]
	global_load_lds_dwordx4 v[66:67], off offset:1024
	v_mfma_f32_32x32x16_bf16 v[0:15], v[184:187], v[192:195], v[0:15]
	s_waitcnt vmcnt(8)
	s_waitcnt lgkmcnt(0)
	s_barrier
	ds_read_b128 v[160:163], v109 offset:16384
	ds_read_b128 v[168:171], v110 offset:24576
	v_mfma_f32_32x32x16_bf16 v[48:63], v[128:131], v[136:139], v[48:63]
	ds_read_b128 v[172:175], v110 offset:26624
	ds_read_b128 v[164:167], v109 offset:18432
	v_mfma_f32_32x32x16_bf16 v[32:47], v[128:131], v[140:143], v[32:47]
	ds_read_b128 v[176:179], v111 offset:16384
	ds_read_b128 v[188:191], v112 offset:24576
	v_mfma_f32_32x32x16_bf16 v[16:31], v[132:135], v[136:139], v[16:31]
	ds_read_b128 v[192:195], v112 offset:26624
	ds_read_b128 v[184:187], v111 offset:18432
	v_mfma_f32_32x32x16_bf16 v[0:15], v[132:135], v[140:143], v[0:15]
	s_mov_b32 m0, s52
	v_lshl_add_u64 v[64:65], v[64:65], 0, s[44:45]
	global_load_lds_dwordx4 v[64:65], off sc1
	v_mfma_f32_32x32x16_bf16 v[48:63], v[144:147], v[152:155], v[48:63]
	global_load_lds_dwordx4 v[64:65], off offset:1024 sc1
	v_mfma_f32_32x32x16_bf16 v[32:47], v[144:147], v[156:159], v[32:47]
	s_mov_b32 m0, s56
	v_lshl_add_u64 v[66:67], v[66:67], 0, s[44:45]
	global_load_lds_dwordx4 v[66:67], off
	v_mfma_f32_32x32x16_bf16 v[16:31], v[148:151], v[152:155], v[16:31]
	global_load_lds_dwordx4 v[66:67], off offset:1024
	v_mfma_f32_32x32x16_bf16 v[0:15], v[148:151], v[156:159], v[0:15]
	s_waitcnt vmcnt(8)
	s_waitcnt lgkmcnt(0)
	s_barrier
	ds_read_b128 v[128:131], v109 offset:32768
	ds_read_b128 v[136:139], v110 offset:40960
	v_mfma_f32_32x32x16_bf16 v[48:63], v[160:163], v[168:171], v[48:63]
	ds_read_b128 v[140:143], v110 offset:43008
	ds_read_b128 v[132:135], v109 offset:34816
	v_mfma_f32_32x32x16_bf16 v[32:47], v[160:163], v[172:175], v[32:47]
	ds_read_b128 v[144:147], v111 offset:32768
	ds_read_b128 v[152:155], v112 offset:40960
	v_mfma_f32_32x32x16_bf16 v[16:31], v[164:167], v[168:171], v[16:31]
	ds_read_b128 v[156:159], v112 offset:43008
	ds_read_b128 v[148:151], v111 offset:34816
	v_mfma_f32_32x32x16_bf16 v[0:15], v[164:167], v[172:175], v[0:15]
	s_mov_b32 m0, s53
	v_lshl_add_u64 v[64:65], v[64:65], 0, s[44:45]
	global_load_lds_dwordx4 v[64:65], off sc1
	v_mfma_f32_32x32x16_bf16 v[48:63], v[176:179], v[188:191], v[48:63]
	global_load_lds_dwordx4 v[64:65], off offset:1024 sc1
	v_mfma_f32_32x32x16_bf16 v[32:47], v[176:179], v[192:195], v[32:47]
	s_mov_b32 m0, s57
	v_lshl_add_u64 v[66:67], v[66:67], 0, s[44:45]
	global_load_lds_dwordx4 v[66:67], off
	v_mfma_f32_32x32x16_bf16 v[16:31], v[184:187], v[188:191], v[16:31]
	global_load_lds_dwordx4 v[66:67], off offset:1024
	v_mfma_f32_32x32x16_bf16 v[0:15], v[184:187], v[192:195], v[0:15]
	s_waitcnt vmcnt(8)
	s_waitcnt lgkmcnt(0)
	s_barrier
	ds_read_b128 v[160:163], v109 offset:49152
	ds_read_b128 v[168:171], v110 offset:57344
	v_mfma_f32_32x32x16_bf16 v[48:63], v[128:131], v[136:139], v[48:63]
	ds_read_b128 v[172:175], v110 offset:59392
	ds_read_b128 v[164:167], v109 offset:51200
	v_mfma_f32_32x32x16_bf16 v[32:47], v[128:131], v[140:143], v[32:47]
	ds_read_b128 v[176:179], v111 offset:49152
	ds_read_b128 v[188:191], v112 offset:57344
	v_mfma_f32_32x32x16_bf16 v[16:31], v[132:135], v[136:139], v[16:31]
	ds_read_b128 v[192:195], v112 offset:59392
	ds_read_b128 v[184:187], v111 offset:51200
	v_mfma_f32_32x32x16_bf16 v[0:15], v[132:135], v[140:143], v[0:15]
	s_mov_b32 m0, s54
	v_lshl_add_u64 v[64:65], v[64:65], 0, s[44:45]
	global_load_lds_dwordx4 v[64:65], off sc1
	v_mfma_f32_32x32x16_bf16 v[48:63], v[144:147], v[152:155], v[48:63]
	global_load_lds_dwordx4 v[64:65], off offset:1024 sc1
	v_mfma_f32_32x32x16_bf16 v[32:47], v[144:147], v[156:159], v[32:47]
	s_mov_b32 m0, s58
	v_lshl_add_u64 v[66:67], v[66:67], 0, s[44:45]
	global_load_lds_dwordx4 v[66:67], off
	v_mfma_f32_32x32x16_bf16 v[16:31], v[148:151], v[152:155], v[16:31]
	global_load_lds_dwordx4 v[66:67], off offset:1024
	v_mfma_f32_32x32x16_bf16 v[0:15], v[148:151], v[156:159], v[0:15]
	s_waitcnt vmcnt(8)
	s_waitcnt lgkmcnt(0)
	s_barrier
	ds_read_b128 v[128:131], v109
	ds_read_b128 v[136:139], v110 offset:8192
	v_mfma_f32_32x32x16_bf16 v[48:63], v[160:163], v[168:171], v[48:63]
	ds_read_b128 v[140:143], v110 offset:10240
	ds_read_b128 v[132:135], v109 offset:2048
	v_mfma_f32_32x32x16_bf16 v[32:47], v[160:163], v[172:175], v[32:47]
	ds_read_b128 v[144:147], v111
	ds_read_b128 v[152:155], v112 offset:8192
	v_mfma_f32_32x32x16_bf16 v[16:31], v[164:167], v[168:171], v[16:31]
	ds_read_b128 v[156:159], v112 offset:10240
	ds_read_b128 v[148:151], v111 offset:2048
	v_mfma_f32_32x32x16_bf16 v[0:15], v[164:167], v[172:175], v[0:15]
	s_mov_b32 m0, s55
	v_lshl_add_u64 v[64:65], v[64:65], 0, s[44:45]
	global_load_lds_dwordx4 v[64:65], off sc1
	v_mfma_f32_32x32x16_bf16 v[48:63], v[176:179], v[188:191], v[48:63]
	global_load_lds_dwordx4 v[64:65], off offset:1024 sc1
	v_mfma_f32_32x32x16_bf16 v[32:47], v[176:179], v[192:195], v[32:47]
	s_mov_b32 m0, s59
	v_lshl_add_u64 v[66:67], v[66:67], 0, s[44:45]
	global_load_lds_dwordx4 v[66:67], off
	v_mfma_f32_32x32x16_bf16 v[16:31], v[184:187], v[188:191], v[16:31]
	global_load_lds_dwordx4 v[66:67], off offset:1024
	v_mfma_f32_32x32x16_bf16 v[0:15], v[184:187], v[192:195], v[0:15]
	s_waitcnt vmcnt(8)
	s_waitcnt lgkmcnt(0)
	s_barrier
	ds_read_b128 v[160:163], v109 offset:16384
	ds_read_b128 v[168:171], v110 offset:24576
	v_mfma_f32_32x32x16_bf16 v[48:63], v[128:131], v[136:139], v[48:63]
	ds_read_b128 v[172:175], v110 offset:26624
	ds_read_b128 v[164:167], v109 offset:18432
	v_mfma_f32_32x32x16_bf16 v[32:47], v[128:131], v[140:143], v[32:47]
	ds_read_b128 v[176:179], v111 offset:16384
	ds_read_b128 v[188:191], v112 offset:24576
	v_mfma_f32_32x32x16_bf16 v[16:31], v[132:135], v[136:139], v[16:31]
	ds_read_b128 v[192:195], v112 offset:26624
	ds_read_b128 v[184:187], v111 offset:18432
	v_mfma_f32_32x32x16_bf16 v[0:15], v[132:135], v[140:143], v[0:15]
	s_mov_b32 m0, s52
	v_lshl_add_u64 v[64:65], v[64:65], 0, s[44:45]
	global_load_lds_dwordx4 v[64:65], off sc1
	v_mfma_f32_32x32x16_bf16 v[48:63], v[144:147], v[152:155], v[48:63]
	global_load_lds_dwordx4 v[64:65], off offset:1024 sc1
	v_mfma_f32_32x32x16_bf16 v[32:47], v[144:147], v[156:159], v[32:47]
	s_mov_b32 m0, s56
	v_lshl_add_u64 v[66:67], v[66:67], 0, s[44:45]
	global_load_lds_dwordx4 v[66:67], off
	v_mfma_f32_32x32x16_bf16 v[16:31], v[148:151], v[152:155], v[16:31]
	global_load_lds_dwordx4 v[66:67], off offset:1024
	v_mfma_f32_32x32x16_bf16 v[0:15], v[148:151], v[156:159], v[0:15]
	s_waitcnt vmcnt(8)
	s_waitcnt lgkmcnt(0)
	s_barrier
	ds_read_b128 v[128:131], v109 offset:32768
	ds_read_b128 v[136:139], v110 offset:40960
	v_mfma_f32_32x32x16_bf16 v[48:63], v[160:163], v[168:171], v[48:63]
	ds_read_b128 v[140:143], v110 offset:43008
	ds_read_b128 v[132:135], v109 offset:34816
	v_mfma_f32_32x32x16_bf16 v[32:47], v[160:163], v[172:175], v[32:47]
	ds_read_b128 v[144:147], v111 offset:32768
	ds_read_b128 v[152:155], v112 offset:40960
	v_mfma_f32_32x32x16_bf16 v[16:31], v[164:167], v[168:171], v[16:31]
	ds_read_b128 v[156:159], v112 offset:43008
	ds_read_b128 v[148:151], v111 offset:34816
	v_mfma_f32_32x32x16_bf16 v[0:15], v[164:167], v[172:175], v[0:15]
	s_mov_b32 m0, s53
	v_lshl_add_u64 v[64:65], v[64:65], 0, s[44:45]
	global_load_lds_dwordx4 v[64:65], off sc1
	v_mfma_f32_32x32x16_bf16 v[48:63], v[176:179], v[188:191], v[48:63]
	global_load_lds_dwordx4 v[64:65], off offset:1024 sc1
	v_mfma_f32_32x32x16_bf16 v[32:47], v[176:179], v[192:195], v[32:47]
	s_mov_b32 m0, s57
	v_lshl_add_u64 v[66:67], v[66:67], 0, s[44:45]
	global_load_lds_dwordx4 v[66:67], off
	v_mfma_f32_32x32x16_bf16 v[16:31], v[184:187], v[188:191], v[16:31]
	global_load_lds_dwordx4 v[66:67], off offset:1024
	v_mfma_f32_32x32x16_bf16 v[0:15], v[184:187], v[192:195], v[0:15]
	s_waitcnt vmcnt(8)
	s_waitcnt lgkmcnt(0)
	s_barrier
	ds_read_b128 v[160:163], v109 offset:49152
	ds_read_b128 v[168:171], v110 offset:57344
	v_mfma_f32_32x32x16_bf16 v[48:63], v[128:131], v[136:139], v[48:63]
	ds_read_b128 v[172:175], v110 offset:59392
	ds_read_b128 v[164:167], v109 offset:51200
	v_mfma_f32_32x32x16_bf16 v[32:47], v[128:131], v[140:143], v[32:47]
	ds_read_b128 v[176:179], v111 offset:49152
	ds_read_b128 v[188:191], v112 offset:57344
	v_mfma_f32_32x32x16_bf16 v[16:31], v[132:135], v[136:139], v[16:31]
	ds_read_b128 v[192:195], v112 offset:59392
	ds_read_b128 v[184:187], v111 offset:51200
	v_mfma_f32_32x32x16_bf16 v[0:15], v[132:135], v[140:143], v[0:15]
	s_mov_b32 m0, s54
	v_lshl_add_u64 v[64:65], v[64:65], 0, s[44:45]
	global_load_lds_dwordx4 v[64:65], off sc1
	v_mfma_f32_32x32x16_bf16 v[48:63], v[144:147], v[152:155], v[48:63]
	global_load_lds_dwordx4 v[64:65], off offset:1024 sc1
	v_mfma_f32_32x32x16_bf16 v[32:47], v[144:147], v[156:159], v[32:47]
	s_mov_b32 m0, s58
	v_lshl_add_u64 v[66:67], v[66:67], 0, s[44:45]
	global_load_lds_dwordx4 v[66:67], off
	v_mfma_f32_32x32x16_bf16 v[16:31], v[148:151], v[152:155], v[16:31]
	global_load_lds_dwordx4 v[66:67], off offset:1024
	v_mfma_f32_32x32x16_bf16 v[0:15], v[148:151], v[156:159], v[0:15]
	s_waitcnt vmcnt(8)
	s_waitcnt lgkmcnt(0)
	s_barrier
	ds_read_b128 v[128:131], v109
	ds_read_b128 v[136:139], v110 offset:8192
	v_mfma_f32_32x32x16_bf16 v[48:63], v[160:163], v[168:171], v[48:63]
	ds_read_b128 v[140:143], v110 offset:10240
	ds_read_b128 v[132:135], v109 offset:2048
	v_mfma_f32_32x32x16_bf16 v[32:47], v[160:163], v[172:175], v[32:47]
	ds_read_b128 v[144:147], v111
	ds_read_b128 v[152:155], v112 offset:8192
	v_mfma_f32_32x32x16_bf16 v[16:31], v[164:167], v[168:171], v[16:31]
	ds_read_b128 v[156:159], v112 offset:10240
	ds_read_b128 v[148:151], v111 offset:2048
	v_mfma_f32_32x32x16_bf16 v[0:15], v[164:167], v[172:175], v[0:15]
	s_mov_b32 m0, s55
	v_lshl_add_u64 v[64:65], v[64:65], 0, s[44:45]
	global_load_lds_dwordx4 v[64:65], off sc1
	v_mfma_f32_32x32x16_bf16 v[48:63], v[176:179], v[188:191], v[48:63]
	global_load_lds_dwordx4 v[64:65], off offset:1024 sc1
	v_mfma_f32_32x32x16_bf16 v[32:47], v[176:179], v[192:195], v[32:47]
	s_mov_b32 m0, s59
	v_lshl_add_u64 v[66:67], v[66:67], 0, s[44:45]
	global_load_lds_dwordx4 v[66:67], off
	v_mfma_f32_32x32x16_bf16 v[16:31], v[184:187], v[188:191], v[16:31]
	global_load_lds_dwordx4 v[66:67], off offset:1024
	v_mfma_f32_32x32x16_bf16 v[0:15], v[184:187], v[192:195], v[0:15]
	s_waitcnt vmcnt(8)
	s_waitcnt lgkmcnt(0)
	s_barrier
	ds_read_b128 v[160:163], v109 offset:16384
	ds_read_b128 v[168:171], v110 offset:24576
	v_mfma_f32_32x32x16_bf16 v[48:63], v[128:131], v[136:139], v[48:63]
	ds_read_b128 v[172:175], v110 offset:26624
	ds_read_b128 v[164:167], v109 offset:18432
	v_mfma_f32_32x32x16_bf16 v[32:47], v[128:131], v[140:143], v[32:47]
	ds_read_b128 v[176:179], v111 offset:16384
	ds_read_b128 v[188:191], v112 offset:24576
	v_mfma_f32_32x32x16_bf16 v[16:31], v[132:135], v[136:139], v[16:31]
	ds_read_b128 v[192:195], v112 offset:26624
	ds_read_b128 v[184:187], v111 offset:18432
	v_mfma_f32_32x32x16_bf16 v[0:15], v[132:135], v[140:143], v[0:15]
	s_mov_b32 m0, s52
	v_lshl_add_u64 v[64:65], v[64:65], 0, s[44:45]
	global_load_lds_dwordx4 v[64:65], off sc1
	v_mfma_f32_32x32x16_bf16 v[48:63], v[144:147], v[152:155], v[48:63]
	global_load_lds_dwordx4 v[64:65], off offset:1024 sc1
	v_mfma_f32_32x32x16_bf16 v[32:47], v[144:147], v[156:159], v[32:47]
	s_mov_b32 m0, s56
	v_lshl_add_u64 v[66:67], v[66:67], 0, s[44:45]
	global_load_lds_dwordx4 v[66:67], off
	v_mfma_f32_32x32x16_bf16 v[16:31], v[148:151], v[152:155], v[16:31]
	global_load_lds_dwordx4 v[66:67], off offset:1024
	v_mfma_f32_32x32x16_bf16 v[0:15], v[148:151], v[156:159], v[0:15]
	s_waitcnt vmcnt(8)
	s_waitcnt lgkmcnt(0)
	s_barrier
	ds_read_b128 v[128:131], v109 offset:32768
	ds_read_b128 v[136:139], v110 offset:40960
	v_mfma_f32_32x32x16_bf16 v[48:63], v[160:163], v[168:171], v[48:63]
	ds_read_b128 v[140:143], v110 offset:43008
	ds_read_b128 v[132:135], v109 offset:34816
	v_mfma_f32_32x32x16_bf16 v[32:47], v[160:163], v[172:175], v[32:47]
	ds_read_b128 v[144:147], v111 offset:32768
	ds_read_b128 v[152:155], v112 offset:40960
	v_mfma_f32_32x32x16_bf16 v[16:31], v[164:167], v[168:171], v[16:31]
	ds_read_b128 v[156:159], v112 offset:43008
	ds_read_b128 v[148:151], v111 offset:34816
	v_mfma_f32_32x32x16_bf16 v[0:15], v[164:167], v[172:175], v[0:15]
	s_mov_b32 m0, s53
	v_lshl_add_u64 v[64:65], v[64:65], 0, s[44:45]
	global_load_lds_dwordx4 v[64:65], off sc1
	v_mfma_f32_32x32x16_bf16 v[48:63], v[176:179], v[188:191], v[48:63]
	global_load_lds_dwordx4 v[64:65], off offset:1024 sc1
	v_mfma_f32_32x32x16_bf16 v[32:47], v[176:179], v[192:195], v[32:47]
	s_mov_b32 m0, s57
	v_lshl_add_u64 v[66:67], v[66:67], 0, s[44:45]
	global_load_lds_dwordx4 v[66:67], off
	v_mfma_f32_32x32x16_bf16 v[16:31], v[184:187], v[188:191], v[16:31]
	global_load_lds_dwordx4 v[66:67], off offset:1024
	v_mfma_f32_32x32x16_bf16 v[0:15], v[184:187], v[192:195], v[0:15]
	s_waitcnt vmcnt(8)
	s_waitcnt lgkmcnt(0)
	s_barrier
	ds_read_b128 v[160:163], v109 offset:49152
	ds_read_b128 v[168:171], v110 offset:57344
	v_mfma_f32_32x32x16_bf16 v[48:63], v[128:131], v[136:139], v[48:63]
	ds_read_b128 v[172:175], v110 offset:59392
	ds_read_b128 v[164:167], v109 offset:51200
	v_mfma_f32_32x32x16_bf16 v[32:47], v[128:131], v[140:143], v[32:47]
	ds_read_b128 v[176:179], v111 offset:49152
	ds_read_b128 v[188:191], v112 offset:57344
	v_mfma_f32_32x32x16_bf16 v[16:31], v[132:135], v[136:139], v[16:31]
	ds_read_b128 v[192:195], v112 offset:59392
	ds_read_b128 v[184:187], v111 offset:51200
	v_mfma_f32_32x32x16_bf16 v[0:15], v[132:135], v[140:143], v[0:15]
	s_mov_b32 m0, s54
	v_lshl_add_u64 v[64:65], v[64:65], 0, s[44:45]
	global_load_lds_dwordx4 v[64:65], off sc1
	v_mfma_f32_32x32x16_bf16 v[48:63], v[144:147], v[152:155], v[48:63]
	global_load_lds_dwordx4 v[64:65], off offset:1024 sc1
	v_mfma_f32_32x32x16_bf16 v[32:47], v[144:147], v[156:159], v[32:47]
	s_mov_b32 m0, s58
	v_lshl_add_u64 v[66:67], v[66:67], 0, s[44:45]
	global_load_lds_dwordx4 v[66:67], off
	v_mfma_f32_32x32x16_bf16 v[16:31], v[148:151], v[152:155], v[16:31]
	global_load_lds_dwordx4 v[66:67], off offset:1024
	v_mfma_f32_32x32x16_bf16 v[0:15], v[148:151], v[156:159], v[0:15]
	s_waitcnt vmcnt(8)
	s_waitcnt lgkmcnt(0)
	s_barrier
	ds_read_b128 v[128:131], v109
	ds_read_b128 v[136:139], v110 offset:8192
	v_mfma_f32_32x32x16_bf16 v[48:63], v[160:163], v[168:171], v[48:63]
	ds_read_b128 v[140:143], v110 offset:10240
	ds_read_b128 v[132:135], v109 offset:2048
	v_mfma_f32_32x32x16_bf16 v[32:47], v[160:163], v[172:175], v[32:47]
	ds_read_b128 v[144:147], v111
	ds_read_b128 v[152:155], v112 offset:8192
	v_mfma_f32_32x32x16_bf16 v[16:31], v[164:167], v[168:171], v[16:31]
	ds_read_b128 v[156:159], v112 offset:10240
	ds_read_b128 v[148:151], v111 offset:2048
	v_mfma_f32_32x32x16_bf16 v[0:15], v[164:167], v[172:175], v[0:15]
	s_mov_b32 m0, s55
	v_lshl_add_u64 v[64:65], v[64:65], 0, s[44:45]
	global_load_lds_dwordx4 v[64:65], off sc1
	v_mfma_f32_32x32x16_bf16 v[48:63], v[176:179], v[188:191], v[48:63]
	global_load_lds_dwordx4 v[64:65], off offset:1024 sc1
	v_mfma_f32_32x32x16_bf16 v[32:47], v[176:179], v[192:195], v[32:47]
	s_mov_b32 m0, s59
	v_lshl_add_u64 v[66:67], v[66:67], 0, s[44:45]
	global_load_lds_dwordx4 v[66:67], off
	v_mfma_f32_32x32x16_bf16 v[16:31], v[184:187], v[188:191], v[16:31]
	global_load_lds_dwordx4 v[66:67], off offset:1024
	v_mfma_f32_32x32x16_bf16 v[0:15], v[184:187], v[192:195], v[0:15]
	s_waitcnt vmcnt(8)
	s_waitcnt lgkmcnt(0)
	s_barrier
	ds_read_b128 v[160:163], v109 offset:16384
	ds_read_b128 v[168:171], v110 offset:24576
	v_mfma_f32_32x32x16_bf16 v[48:63], v[128:131], v[136:139], v[48:63]
	ds_read_b128 v[172:175], v110 offset:26624
	ds_read_b128 v[164:167], v109 offset:18432
	v_mfma_f32_32x32x16_bf16 v[32:47], v[128:131], v[140:143], v[32:47]
	ds_read_b128 v[176:179], v111 offset:16384
	ds_read_b128 v[188:191], v112 offset:24576
	v_mfma_f32_32x32x16_bf16 v[16:31], v[132:135], v[136:139], v[16:31]
	ds_read_b128 v[192:195], v112 offset:26624
	ds_read_b128 v[184:187], v111 offset:18432
	v_mfma_f32_32x32x16_bf16 v[0:15], v[132:135], v[140:143], v[0:15]
	s_mov_b32 m0, s52
	v_lshl_add_u64 v[64:65], v[64:65], 0, s[44:45]
	global_load_lds_dwordx4 v[64:65], off sc1
	v_mfma_f32_32x32x16_bf16 v[48:63], v[144:147], v[152:155], v[48:63]
	global_load_lds_dwordx4 v[64:65], off offset:1024 sc1
	v_mfma_f32_32x32x16_bf16 v[32:47], v[144:147], v[156:159], v[32:47]
	s_mov_b32 m0, s56
	v_lshl_add_u64 v[66:67], v[66:67], 0, s[44:45]
	global_load_lds_dwordx4 v[66:67], off
	v_mfma_f32_32x32x16_bf16 v[16:31], v[148:151], v[152:155], v[16:31]
	global_load_lds_dwordx4 v[66:67], off offset:1024
	v_mfma_f32_32x32x16_bf16 v[0:15], v[148:151], v[156:159], v[0:15]
	s_waitcnt vmcnt(8)
	s_waitcnt lgkmcnt(0)
	s_barrier
	ds_read_b128 v[128:131], v109 offset:32768
	ds_read_b128 v[136:139], v110 offset:40960
	v_mfma_f32_32x32x16_bf16 v[48:63], v[160:163], v[168:171], v[48:63]
	ds_read_b128 v[140:143], v110 offset:43008
	ds_read_b128 v[132:135], v109 offset:34816
	v_mfma_f32_32x32x16_bf16 v[32:47], v[160:163], v[172:175], v[32:47]
	ds_read_b128 v[144:147], v111 offset:32768
	ds_read_b128 v[152:155], v112 offset:40960
	v_mfma_f32_32x32x16_bf16 v[16:31], v[164:167], v[168:171], v[16:31]
	ds_read_b128 v[156:159], v112 offset:43008
	ds_read_b128 v[148:151], v111 offset:34816
	v_mfma_f32_32x32x16_bf16 v[0:15], v[164:167], v[172:175], v[0:15]
	s_mov_b32 m0, s53
	v_lshl_add_u64 v[64:65], v[64:65], 0, s[44:45]
	global_load_lds_dwordx4 v[64:65], off sc1
	v_mfma_f32_32x32x16_bf16 v[48:63], v[176:179], v[188:191], v[48:63]
	global_load_lds_dwordx4 v[64:65], off offset:1024 sc1
	v_mfma_f32_32x32x16_bf16 v[32:47], v[176:179], v[192:195], v[32:47]
	s_mov_b32 m0, s57
	v_lshl_add_u64 v[66:67], v[66:67], 0, s[44:45]
	global_load_lds_dwordx4 v[66:67], off
	v_mfma_f32_32x32x16_bf16 v[16:31], v[184:187], v[188:191], v[16:31]
	global_load_lds_dwordx4 v[66:67], off offset:1024
	v_mfma_f32_32x32x16_bf16 v[0:15], v[184:187], v[192:195], v[0:15]
	s_waitcnt vmcnt(8)
	s_waitcnt lgkmcnt(0)
	s_barrier
	ds_read_b128 v[160:163], v109 offset:49152
	ds_read_b128 v[168:171], v110 offset:57344
	v_mfma_f32_32x32x16_bf16 v[48:63], v[128:131], v[136:139], v[48:63]
	ds_read_b128 v[172:175], v110 offset:59392
	ds_read_b128 v[164:167], v109 offset:51200
	v_mfma_f32_32x32x16_bf16 v[32:47], v[128:131], v[140:143], v[32:47]
	ds_read_b128 v[176:179], v111 offset:49152
	ds_read_b128 v[188:191], v112 offset:57344
	v_mfma_f32_32x32x16_bf16 v[16:31], v[132:135], v[136:139], v[16:31]
	ds_read_b128 v[192:195], v112 offset:59392
	ds_read_b128 v[184:187], v111 offset:51200
	v_mfma_f32_32x32x16_bf16 v[0:15], v[132:135], v[140:143], v[0:15]
	s_mov_b32 m0, s54
	v_lshl_add_u64 v[64:65], v[64:65], 0, s[44:45]
	global_load_lds_dwordx4 v[64:65], off sc1
	v_mfma_f32_32x32x16_bf16 v[48:63], v[144:147], v[152:155], v[48:63]
	global_load_lds_dwordx4 v[64:65], off offset:1024 sc1
	v_mfma_f32_32x32x16_bf16 v[32:47], v[144:147], v[156:159], v[32:47]
	s_mov_b32 m0, s58
	v_lshl_add_u64 v[66:67], v[66:67], 0, s[44:45]
	global_load_lds_dwordx4 v[66:67], off
	v_mfma_f32_32x32x16_bf16 v[16:31], v[148:151], v[152:155], v[16:31]
	global_load_lds_dwordx4 v[66:67], off offset:1024
	v_mfma_f32_32x32x16_bf16 v[0:15], v[148:151], v[156:159], v[0:15]
	s_waitcnt vmcnt(8)
	s_waitcnt lgkmcnt(0)
	s_barrier
	ds_read_b128 v[128:131], v109
	ds_read_b128 v[136:139], v110 offset:8192
	v_mfma_f32_32x32x16_bf16 v[48:63], v[160:163], v[168:171], v[48:63]
	ds_read_b128 v[140:143], v110 offset:10240
	ds_read_b128 v[132:135], v109 offset:2048
	v_mfma_f32_32x32x16_bf16 v[32:47], v[160:163], v[172:175], v[32:47]
	ds_read_b128 v[144:147], v111
	ds_read_b128 v[152:155], v112 offset:8192
	v_mfma_f32_32x32x16_bf16 v[16:31], v[164:167], v[168:171], v[16:31]
	ds_read_b128 v[156:159], v112 offset:10240
	ds_read_b128 v[148:151], v111 offset:2048
	v_mfma_f32_32x32x16_bf16 v[0:15], v[164:167], v[172:175], v[0:15]
	s_mov_b32 m0, s55
	v_lshl_add_u64 v[64:65], v[64:65], 0, s[44:45]
	global_load_lds_dwordx4 v[64:65], off sc1
	v_mfma_f32_32x32x16_bf16 v[48:63], v[176:179], v[188:191], v[48:63]
	global_load_lds_dwordx4 v[64:65], off offset:1024 sc1
	v_mfma_f32_32x32x16_bf16 v[32:47], v[176:179], v[192:195], v[32:47]
	s_mov_b32 m0, s59
	v_lshl_add_u64 v[66:67], v[66:67], 0, s[44:45]
	global_load_lds_dwordx4 v[66:67], off
	v_mfma_f32_32x32x16_bf16 v[16:31], v[184:187], v[188:191], v[16:31]
	global_load_lds_dwordx4 v[66:67], off offset:1024
	v_mfma_f32_32x32x16_bf16 v[0:15], v[184:187], v[192:195], v[0:15]
	s_waitcnt vmcnt(8)
	s_waitcnt lgkmcnt(0)
	s_barrier
	ds_read_b128 v[160:163], v109 offset:16384
	ds_read_b128 v[168:171], v110 offset:24576
	v_mfma_f32_32x32x16_bf16 v[48:63], v[128:131], v[136:139], v[48:63]
	ds_read_b128 v[172:175], v110 offset:26624
	ds_read_b128 v[164:167], v109 offset:18432
	v_mfma_f32_32x32x16_bf16 v[32:47], v[128:131], v[140:143], v[32:47]
	ds_read_b128 v[176:179], v111 offset:16384
	ds_read_b128 v[188:191], v112 offset:24576
	v_mfma_f32_32x32x16_bf16 v[16:31], v[132:135], v[136:139], v[16:31]
	ds_read_b128 v[192:195], v112 offset:26624
	ds_read_b128 v[184:187], v111 offset:18432
	v_mfma_f32_32x32x16_bf16 v[0:15], v[132:135], v[140:143], v[0:15]
	s_mov_b32 m0, s52
	v_lshl_add_u64 v[64:65], v[64:65], 0, s[44:45]
	global_load_lds_dwordx4 v[64:65], off sc1
	v_mfma_f32_32x32x16_bf16 v[48:63], v[144:147], v[152:155], v[48:63]
	global_load_lds_dwordx4 v[64:65], off offset:1024 sc1
	v_mfma_f32_32x32x16_bf16 v[32:47], v[144:147], v[156:159], v[32:47]
	s_mov_b32 m0, s56
	v_lshl_add_u64 v[66:67], v[66:67], 0, s[44:45]
	global_load_lds_dwordx4 v[66:67], off
	v_mfma_f32_32x32x16_bf16 v[16:31], v[148:151], v[152:155], v[16:31]
	global_load_lds_dwordx4 v[66:67], off offset:1024
	v_mfma_f32_32x32x16_bf16 v[0:15], v[148:151], v[156:159], v[0:15]
	s_waitcnt vmcnt(8)
	s_waitcnt lgkmcnt(0)
	s_barrier
	ds_read_b128 v[128:131], v109 offset:32768
	ds_read_b128 v[136:139], v110 offset:40960
	v_mfma_f32_32x32x16_bf16 v[48:63], v[160:163], v[168:171], v[48:63]
	ds_read_b128 v[140:143], v110 offset:43008
	ds_read_b128 v[132:135], v109 offset:34816
	v_mfma_f32_32x32x16_bf16 v[32:47], v[160:163], v[172:175], v[32:47]
	ds_read_b128 v[144:147], v111 offset:32768
	ds_read_b128 v[152:155], v112 offset:40960
	v_mfma_f32_32x32x16_bf16 v[16:31], v[164:167], v[168:171], v[16:31]
	ds_read_b128 v[156:159], v112 offset:43008
	ds_read_b128 v[148:151], v111 offset:34816
	v_mfma_f32_32x32x16_bf16 v[0:15], v[164:167], v[172:175], v[0:15]
	s_mov_b32 m0, s53
	v_lshl_add_u64 v[64:65], v[64:65], 0, s[44:45]
	global_load_lds_dwordx4 v[64:65], off sc1
	v_mfma_f32_32x32x16_bf16 v[48:63], v[176:179], v[188:191], v[48:63]
	global_load_lds_dwordx4 v[64:65], off offset:1024 sc1
	v_mfma_f32_32x32x16_bf16 v[32:47], v[176:179], v[192:195], v[32:47]
	s_mov_b32 m0, s57
	v_lshl_add_u64 v[66:67], v[66:67], 0, s[44:45]
	global_load_lds_dwordx4 v[66:67], off
	v_mfma_f32_32x32x16_bf16 v[16:31], v[184:187], v[188:191], v[16:31]
	global_load_lds_dwordx4 v[66:67], off offset:1024
	v_mfma_f32_32x32x16_bf16 v[0:15], v[184:187], v[192:195], v[0:15]
	s_waitcnt vmcnt(8)
	s_waitcnt lgkmcnt(0)
	s_barrier
	ds_read_b128 v[160:163], v109 offset:49152
	ds_read_b128 v[168:171], v110 offset:57344
	v_mfma_f32_32x32x16_bf16 v[48:63], v[128:131], v[136:139], v[48:63]
	ds_read_b128 v[172:175], v110 offset:59392
	ds_read_b128 v[164:167], v109 offset:51200
	v_mfma_f32_32x32x16_bf16 v[32:47], v[128:131], v[140:143], v[32:47]
	ds_read_b128 v[176:179], v111 offset:49152
	ds_read_b128 v[188:191], v112 offset:57344
	v_mfma_f32_32x32x16_bf16 v[16:31], v[132:135], v[136:139], v[16:31]
	ds_read_b128 v[192:195], v112 offset:59392
	ds_read_b128 v[184:187], v111 offset:51200
	v_mfma_f32_32x32x16_bf16 v[0:15], v[132:135], v[140:143], v[0:15]
	s_mov_b32 m0, s54
	v_lshl_add_u64 v[64:65], v[64:65], 0, s[44:45]
	global_load_lds_dwordx4 v[64:65], off sc1
	v_mfma_f32_32x32x16_bf16 v[48:63], v[144:147], v[152:155], v[48:63]
	global_load_lds_dwordx4 v[64:65], off offset:1024 sc1
	v_mfma_f32_32x32x16_bf16 v[32:47], v[144:147], v[156:159], v[32:47]
	s_mov_b32 m0, s58
	v_lshl_add_u64 v[66:67], v[66:67], 0, s[44:45]
	global_load_lds_dwordx4 v[66:67], off
	v_mfma_f32_32x32x16_bf16 v[16:31], v[148:151], v[152:155], v[16:31]
	global_load_lds_dwordx4 v[66:67], off offset:1024
	v_mfma_f32_32x32x16_bf16 v[0:15], v[148:151], v[156:159], v[0:15]
	s_waitcnt vmcnt(8)
	s_waitcnt lgkmcnt(0)
	s_barrier
	ds_read_b128 v[128:131], v109
	ds_read_b128 v[136:139], v110 offset:8192
	v_mfma_f32_32x32x16_bf16 v[48:63], v[160:163], v[168:171], v[48:63]
	ds_read_b128 v[140:143], v110 offset:10240
	ds_read_b128 v[132:135], v109 offset:2048
	v_mfma_f32_32x32x16_bf16 v[32:47], v[160:163], v[172:175], v[32:47]
	ds_read_b128 v[144:147], v111
	ds_read_b128 v[152:155], v112 offset:8192
	v_mfma_f32_32x32x16_bf16 v[16:31], v[164:167], v[168:171], v[16:31]
	ds_read_b128 v[156:159], v112 offset:10240
	ds_read_b128 v[148:151], v111 offset:2048
	v_mfma_f32_32x32x16_bf16 v[0:15], v[164:167], v[172:175], v[0:15]
	s_mov_b32 m0, s55
	v_lshl_add_u64 v[64:65], v[64:65], 0, s[44:45]
	global_load_lds_dwordx4 v[64:65], off sc1
	v_mfma_f32_32x32x16_bf16 v[48:63], v[176:179], v[188:191], v[48:63]
	global_load_lds_dwordx4 v[64:65], off offset:1024 sc1
	v_mfma_f32_32x32x16_bf16 v[32:47], v[176:179], v[192:195], v[32:47]
	s_mov_b32 m0, s59
	v_lshl_add_u64 v[66:67], v[66:67], 0, s[44:45]
	global_load_lds_dwordx4 v[66:67], off
	v_mfma_f32_32x32x16_bf16 v[16:31], v[184:187], v[188:191], v[16:31]
	global_load_lds_dwordx4 v[66:67], off offset:1024
	v_mfma_f32_32x32x16_bf16 v[0:15], v[184:187], v[192:195], v[0:15]
	s_waitcnt vmcnt(8)
	s_waitcnt lgkmcnt(0)
	s_barrier
	ds_read_b128 v[160:163], v109 offset:16384
	ds_read_b128 v[168:171], v110 offset:24576
	v_mfma_f32_32x32x16_bf16 v[48:63], v[128:131], v[136:139], v[48:63]
	ds_read_b128 v[172:175], v110 offset:26624
	ds_read_b128 v[164:167], v109 offset:18432
	v_mfma_f32_32x32x16_bf16 v[32:47], v[128:131], v[140:143], v[32:47]
	ds_read_b128 v[176:179], v111 offset:16384
	ds_read_b128 v[188:191], v112 offset:24576
	v_mfma_f32_32x32x16_bf16 v[16:31], v[132:135], v[136:139], v[16:31]
	ds_read_b128 v[192:195], v112 offset:26624
	ds_read_b128 v[184:187], v111 offset:18432
	v_mfma_f32_32x32x16_bf16 v[0:15], v[132:135], v[140:143], v[0:15]
	s_mov_b32 m0, s52
	v_lshl_add_u64 v[64:65], v[64:65], 0, s[44:45]
	global_load_lds_dwordx4 v[64:65], off sc1
	v_mfma_f32_32x32x16_bf16 v[48:63], v[144:147], v[152:155], v[48:63]
	global_load_lds_dwordx4 v[64:65], off offset:1024 sc1
	v_mfma_f32_32x32x16_bf16 v[32:47], v[144:147], v[156:159], v[32:47]
	s_mov_b32 m0, s56
	v_lshl_add_u64 v[66:67], v[66:67], 0, s[44:45]
	global_load_lds_dwordx4 v[66:67], off
	v_mfma_f32_32x32x16_bf16 v[16:31], v[148:151], v[152:155], v[16:31]
	global_load_lds_dwordx4 v[66:67], off offset:1024
	v_mfma_f32_32x32x16_bf16 v[0:15], v[148:151], v[156:159], v[0:15]
	s_waitcnt vmcnt(8)
	s_waitcnt lgkmcnt(0)
	s_barrier
	ds_read_b128 v[128:131], v109 offset:32768
	ds_read_b128 v[136:139], v110 offset:40960
	v_mfma_f32_32x32x16_bf16 v[48:63], v[160:163], v[168:171], v[48:63]
	ds_read_b128 v[140:143], v110 offset:43008
	ds_read_b128 v[132:135], v109 offset:34816
	v_mfma_f32_32x32x16_bf16 v[32:47], v[160:163], v[172:175], v[32:47]
	ds_read_b128 v[144:147], v111 offset:32768
	ds_read_b128 v[152:155], v112 offset:40960
	v_mfma_f32_32x32x16_bf16 v[16:31], v[164:167], v[168:171], v[16:31]
	ds_read_b128 v[156:159], v112 offset:43008
	ds_read_b128 v[148:151], v111 offset:34816
	v_mfma_f32_32x32x16_bf16 v[0:15], v[164:167], v[172:175], v[0:15]
	s_mov_b32 m0, s53
	v_lshl_add_u64 v[64:65], v[64:65], 0, s[44:45]
	global_load_lds_dwordx4 v[64:65], off sc1
	v_mfma_f32_32x32x16_bf16 v[48:63], v[176:179], v[188:191], v[48:63]
	global_load_lds_dwordx4 v[64:65], off offset:1024 sc1
	v_mfma_f32_32x32x16_bf16 v[32:47], v[176:179], v[192:195], v[32:47]
	s_mov_b32 m0, s57
	v_lshl_add_u64 v[66:67], v[66:67], 0, s[44:45]
	global_load_lds_dwordx4 v[66:67], off
	v_mfma_f32_32x32x16_bf16 v[16:31], v[184:187], v[188:191], v[16:31]
	global_load_lds_dwordx4 v[66:67], off offset:1024
	v_mfma_f32_32x32x16_bf16 v[0:15], v[184:187], v[192:195], v[0:15]
	s_waitcnt vmcnt(8)
	s_waitcnt lgkmcnt(0)
	s_barrier
	ds_read_b128 v[160:163], v109 offset:49152
	ds_read_b128 v[168:171], v110 offset:57344
	v_mfma_f32_32x32x16_bf16 v[48:63], v[128:131], v[136:139], v[48:63]
	ds_read_b128 v[172:175], v110 offset:59392
	ds_read_b128 v[164:167], v109 offset:51200
	v_mfma_f32_32x32x16_bf16 v[32:47], v[128:131], v[140:143], v[32:47]
	ds_read_b128 v[176:179], v111 offset:49152
	ds_read_b128 v[188:191], v112 offset:57344
	v_mfma_f32_32x32x16_bf16 v[16:31], v[132:135], v[136:139], v[16:31]
	ds_read_b128 v[192:195], v112 offset:59392
	ds_read_b128 v[184:187], v111 offset:51200
	v_mfma_f32_32x32x16_bf16 v[0:15], v[132:135], v[140:143], v[0:15]
	s_mov_b32 m0, s54
	v_lshl_add_u64 v[64:65], v[64:65], 0, s[44:45]
	global_load_lds_dwordx4 v[64:65], off sc1
	v_mfma_f32_32x32x16_bf16 v[48:63], v[144:147], v[152:155], v[48:63]
	global_load_lds_dwordx4 v[64:65], off offset:1024 sc1
	v_mfma_f32_32x32x16_bf16 v[32:47], v[144:147], v[156:159], v[32:47]
	s_mov_b32 m0, s58
	v_lshl_add_u64 v[66:67], v[66:67], 0, s[44:45]
	global_load_lds_dwordx4 v[66:67], off
	v_mfma_f32_32x32x16_bf16 v[16:31], v[148:151], v[152:155], v[16:31]
	global_load_lds_dwordx4 v[66:67], off offset:1024
	v_mfma_f32_32x32x16_bf16 v[0:15], v[148:151], v[156:159], v[0:15]
	s_waitcnt vmcnt(8)
	s_waitcnt lgkmcnt(0)
	s_barrier
	ds_read_b128 v[128:131], v109
	ds_read_b128 v[136:139], v110 offset:8192
	v_mfma_f32_32x32x16_bf16 v[48:63], v[160:163], v[168:171], v[48:63]
	ds_read_b128 v[140:143], v110 offset:10240
	ds_read_b128 v[132:135], v109 offset:2048
	v_mfma_f32_32x32x16_bf16 v[32:47], v[160:163], v[172:175], v[32:47]
	ds_read_b128 v[144:147], v111
	ds_read_b128 v[152:155], v112 offset:8192
	v_mfma_f32_32x32x16_bf16 v[16:31], v[164:167], v[168:171], v[16:31]
	ds_read_b128 v[156:159], v112 offset:10240
	ds_read_b128 v[148:151], v111 offset:2048
	v_mfma_f32_32x32x16_bf16 v[0:15], v[164:167], v[172:175], v[0:15]
	s_mov_b32 m0, s55
	v_lshl_add_u64 v[64:65], v[64:65], 0, s[44:45]
	global_load_lds_dwordx4 v[64:65], off sc1
	v_mfma_f32_32x32x16_bf16 v[48:63], v[176:179], v[188:191], v[48:63]
	global_load_lds_dwordx4 v[64:65], off offset:1024 sc1
	v_mfma_f32_32x32x16_bf16 v[32:47], v[176:179], v[192:195], v[32:47]
	s_mov_b32 m0, s59
	v_lshl_add_u64 v[66:67], v[66:67], 0, s[44:45]
	global_load_lds_dwordx4 v[66:67], off
	v_mfma_f32_32x32x16_bf16 v[16:31], v[184:187], v[188:191], v[16:31]
	global_load_lds_dwordx4 v[66:67], off offset:1024
	v_mfma_f32_32x32x16_bf16 v[0:15], v[184:187], v[192:195], v[0:15]
	s_waitcnt vmcnt(8)
	s_waitcnt lgkmcnt(0)
	s_barrier
	ds_read_b128 v[160:163], v109 offset:16384
	ds_read_b128 v[168:171], v110 offset:24576
	v_mfma_f32_32x32x16_bf16 v[48:63], v[128:131], v[136:139], v[48:63]
	ds_read_b128 v[172:175], v110 offset:26624
	ds_read_b128 v[164:167], v109 offset:18432
	v_mfma_f32_32x32x16_bf16 v[32:47], v[128:131], v[140:143], v[32:47]
	ds_read_b128 v[176:179], v111 offset:16384
	ds_read_b128 v[188:191], v112 offset:24576
	v_mfma_f32_32x32x16_bf16 v[16:31], v[132:135], v[136:139], v[16:31]
	ds_read_b128 v[192:195], v112 offset:26624
	ds_read_b128 v[184:187], v111 offset:18432
	v_mfma_f32_32x32x16_bf16 v[0:15], v[132:135], v[140:143], v[0:15]
	v_mfma_f32_32x32x16_bf16 v[48:63], v[144:147], v[152:155], v[48:63]
	v_mfma_f32_32x32x16_bf16 v[32:47], v[144:147], v[156:159], v[32:47]
	v_mfma_f32_32x32x16_bf16 v[16:31], v[148:151], v[152:155], v[16:31]
	v_mfma_f32_32x32x16_bf16 v[0:15], v[148:151], v[156:159], v[0:15]
	s_waitcnt vmcnt(4)
	s_waitcnt lgkmcnt(0)
	s_barrier
	ds_read_b128 v[128:131], v109 offset:32768
	ds_read_b128 v[136:139], v110 offset:40960
	v_mfma_f32_32x32x16_bf16 v[48:63], v[160:163], v[168:171], v[48:63]
	ds_read_b128 v[140:143], v110 offset:43008
	ds_read_b128 v[132:135], v109 offset:34816
	v_mfma_f32_32x32x16_bf16 v[32:47], v[160:163], v[172:175], v[32:47]
	ds_read_b128 v[144:147], v111 offset:32768
	ds_read_b128 v[152:155], v112 offset:40960
	v_mfma_f32_32x32x16_bf16 v[16:31], v[164:167], v[168:171], v[16:31]
	ds_read_b128 v[156:159], v112 offset:43008
	ds_read_b128 v[148:151], v111 offset:34816
	v_mfma_f32_32x32x16_bf16 v[0:15], v[164:167], v[172:175], v[0:15]
	v_mfma_f32_32x32x16_bf16 v[48:63], v[176:179], v[188:191], v[48:63]
	v_mfma_f32_32x32x16_bf16 v[32:47], v[176:179], v[192:195], v[32:47]
	v_mfma_f32_32x32x16_bf16 v[16:31], v[184:187], v[188:191], v[16:31]
	v_mfma_f32_32x32x16_bf16 v[0:15], v[184:187], v[192:195], v[0:15]
	s_waitcnt vmcnt(0)
	s_waitcnt lgkmcnt(0)
	s_barrier
	ds_read_b128 v[160:163], v109 offset:49152
	ds_read_b128 v[168:171], v110 offset:57344
	v_mfma_f32_32x32x16_bf16 v[48:63], v[128:131], v[136:139], v[48:63]
	ds_read_b128 v[172:175], v110 offset:59392
	ds_read_b128 v[164:167], v109 offset:51200
	v_mfma_f32_32x32x16_bf16 v[32:47], v[128:131], v[140:143], v[32:47]
	ds_read_b128 v[176:179], v111 offset:49152
	ds_read_b128 v[188:191], v112 offset:57344
	v_mfma_f32_32x32x16_bf16 v[16:31], v[132:135], v[136:139], v[16:31]
	ds_read_b128 v[192:195], v112 offset:59392
	ds_read_b128 v[184:187], v111 offset:51200
	v_mfma_f32_32x32x16_bf16 v[0:15], v[132:135], v[140:143], v[0:15]
	v_mfma_f32_32x32x16_bf16 v[48:63], v[144:147], v[152:155], v[48:63]
	v_mfma_f32_32x32x16_bf16 v[32:47], v[144:147], v[156:159], v[32:47]
	v_mfma_f32_32x32x16_bf16 v[16:31], v[148:151], v[152:155], v[16:31]
	v_mfma_f32_32x32x16_bf16 v[0:15], v[148:151], v[156:159], v[0:15]
	s_waitcnt lgkmcnt(0)
	v_mfma_f32_32x32x16_bf16 v[48:63], v[160:163], v[168:171], v[48:63]
	v_mfma_f32_32x32x16_bf16 v[32:47], v[160:163], v[172:175], v[32:47]
	v_mfma_f32_32x32x16_bf16 v[16:31], v[164:167], v[168:171], v[16:31]
	v_mfma_f32_32x32x16_bf16 v[0:15], v[164:167], v[172:175], v[0:15]
	v_mfma_f32_32x32x16_bf16 v[48:63], v[176:179], v[188:191], v[48:63]
	v_mfma_f32_32x32x16_bf16 v[32:47], v[176:179], v[192:195], v[32:47]
	v_mfma_f32_32x32x16_bf16 v[16:31], v[184:187], v[188:191], v[16:31]
	v_mfma_f32_32x32x16_bf16 v[0:15], v[184:187], v[192:195], v[0:15]

.Lgf_1:
	s_cbranch_vccnz .LBB0_126
	s_ashr_i32 s16, s38, 7
	s_ashr_i32 s17, s16, 31
	s_lshl_b64 s[16:17], s[16:17], 18
	v_lshl_add_u64 v[64:65], v[80:81], 0, s[16:17]
	s_ashr_i32 s16, s35, 7
	s_ashr_i32 s17, s16, 31
	s_lshl_b64 s[16:17], s[16:17], 18
	v_readfirstlane_b32 s1, v88
	v_lshl_add_u64 v[66:67], v[82:83], 0, s[16:17]
	s_mov_b64 s[16:17], 0x400
	s_mov_b32 m0, s1
	v_readfirstlane_b32 s1, v108
	v_lshl_add_u64 v[110:111], v[64:65], 0, s[16:17]
	global_load_lds_dwordx4 v[64:65], off sc1
	s_mov_b32 m0, s1
	v_readfirstlane_b32 s1, v87
	global_load_lds_dwordx4 v[110:111], off sc1
	s_mov_b32 m0, s1
	v_readfirstlane_b32 s1, v79
	global_load_lds_dwordx4 v[66:67], off
	v_lshl_add_u64 v[108:109], v[66:67], 0, s[16:17]
	s_mov_b32 m0, s1
	v_readfirstlane_b32 s1, v78
	global_load_lds_dwordx4 v[108:109], off
	v_lshl_add_u64 v[108:109], v[64:65], 0, s[44:45]
	s_mov_b32 m0, s1
	v_readfirstlane_b32 s1, v77
	global_load_lds_dwordx4 v[108:109], off sc1
	v_lshl_add_u64 v[78:79], v[64:65], 0, s[66:67]
	s_mov_b32 m0, s1
	v_readfirstlane_b32 s1, v76
	global_load_lds_dwordx4 v[78:79], off sc1
	v_lshl_add_u64 v[78:79], v[66:67], 0, s[44:45]
	s_mov_b32 m0, s1
	v_readfirstlane_b32 s1, v75
	global_load_lds_dwordx4 v[78:79], off
	v_lshl_add_u64 v[76:77], v[66:67], 0, s[66:67]
	s_mov_b32 m0, s1
	v_readfirstlane_b32 s1, v74
	global_load_lds_dwordx4 v[76:77], off
	v_lshl_add_u64 v[76:77], v[64:65], 0, s[28:29]
	s_mov_b32 m0, s1
	s_mov_b64 s[16:17], 0x4400
	v_readfirstlane_b32 s1, v73
	global_load_lds_dwordx4 v[76:77], off sc1
	v_lshl_add_u64 v[64:65], v[64:65], 0, s[16:17]
	s_mov_b32 m0, s1
	v_readfirstlane_b32 s1, v71
	global_load_lds_dwordx4 v[64:65], off sc1
	v_lshl_add_u64 v[64:65], v[66:67], 0, s[28:29]
	s_mov_b32 m0, s1
	v_readfirstlane_b32 s1, v70
	global_load_lds_dwordx4 v[64:65], off
	v_lshl_add_u64 v[64:65], v[66:67], 0, s[16:17]
	s_mov_b32 m0, s1
	s_nop 0
	global_load_lds_dwordx4 v[64:65], off
	s_branch .LBB0_126
